# GEMM k-loop: first iteration after an epilogue waits vmcnt(8+S) in phases 1-2 (store acks no longer block the older DMA groups)
# baseline (speedup 1.0000x reference)
.LBB0_253:
	s_add_u32 s6, s84, 0x14000000
	s_addc_u32 s7, s85, 0
	s_lshl_b32 s8, s8, 5
	s_and_b32 s14, s8, 0x60
	s_mov_b64 s[8:9], 0x80
	s_add_i32 m0, s21, 0x18000
	v_lshl_add_u64 v[6:7], v[6:7], 0, s[8:9]
	s_ashr_i32 s40, s82, 31
	s_lshl_b32 s11, s10, 13
	s_lshl_b32 s15, s14, 7
	s_waitcnt vmcnt(2)
	s_barrier
	global_load_lds_dwordx4 v[6:7], off
	v_lshl_add_u64 v[4:5], v[4:5], 0, s[8:9]
	s_add_i32 m0, s21, 0x1a000
	s_add_i32 s41, s21, 0x8000
	s_add_i32 s42, s21, 0xa000
	global_load_lds_dwordx4 v[4:5], off
	v_lshl_add_u64 v[0:1], v[0:1], 0, s[8:9]
	s_mov_b32 m0, s41
	s_add_u32 s12, s24, 0x40080
	global_load_lds_dwordx4 v[0:1], off
	v_lshl_add_u64 v[0:1], v[2:3], 0, s[8:9]
	s_mov_b32 m0, s42
	s_addc_u32 s13, s25, 0
	global_load_lds_dwordx4 v[0:1], off
	s_add_i32 m0, s21, 0x1c000
	v_lshl_add_u64 v[0:1], s[12:13], 0, v[130:131]
	global_load_lds_dwordx4 v[0:1], off
	v_lshl_add_u64 v[0:1], s[12:13], 0, v[134:135]
	s_add_i32 m0, s21, 0x1e000
	s_sext_i32_i16 s46, s0
	global_load_lds_dwordx4 v[0:1], off
	v_and_b32_e32 v0, 15, v182
	v_lshlrev_b32_e32 v1, 1, v11
	v_lshlrev_b32_e32 v2, 6, v182
	s_movk_i32 s0, 0x3c0
	v_lshlrev_b32_e32 v3, 2, v182
	v_and_or_b32 v2, v2, s0, v1
	v_and_b32_e32 v3, 32, v3
	v_lshl_or_b32 v146, s10, 6, v0
	v_lshl_or_b32 v0, v0, 6, v1
	v_lshlrev_b32_e32 v1, 8, v182
	v_bitop3_b32 v147, s15, v2, v3 bitop3:0xf6
	v_and_b32_e32 v1, 0x38000, v1
	v_lshlrev_b32_e32 v2, 11, v10
	v_or3_b32 v1, v8, v1, v2
	v_add_u32_e32 v136, v1, v9
	v_lshlrev_b32_e32 v1, 4, v12
	s_waitcnt vmcnt(6)
	s_cmpk_lt_u32 s1, 0x100
	v_and_b32_e32 v1, 0x78000, v1
	v_bitop3_b32 v0, v0, s11, v3 bitop3:0xde
	s_cselect_b64 s[10:11], -1, 0
	v_or3_b32 v1, v8, v1, v2
	s_add_i32 s43, 0, 0x10000
	s_add_i32 s44, 0, 0x14000
	v_or_b32_e32 v148, s14, v11
	v_mov_b32_e32 v137, v131
	v_add_u32_e32 v138, v1, v9
	v_mov_b32_e32 v139, v131
	v_mov_b64_e32 v[140:141], 0x1600
	v_mov_b64_e32 v[142:143], 0x15ff
	v_add_u32_e32 v149, s43, v147
	v_add_u32_e32 v150, s44, v147
	v_add_u32_e32 v151, 0, v0
	s_movk_i32 s45, 0x1600
	s_barrier
	s_mov_b32 s88, 0
	s_branch .LBB0_256

.LBB0_255:
	s_mov_b32 s88, 1
	s_andn2_b64 vcc, exec, s[0:1]
	s_mov_b32 s46, s12
	s_mov_b32 s20, s14
	s_mov_b64 s[24:25], s[18:19]
	s_mov_b64 s[22:23], s[16:17]
	s_cbranch_vccz .LBB0_265

.LBB0_259:
	ds_read_b128 v[152:155], v149
	ds_read_b128 v[156:159], v149 offset:1024
	ds_read_b128 v[160:163], v149 offset:2048
	ds_read_b128 v[164:167], v149 offset:3072
	ds_read_b128 v[168:171], v150
	ds_read_b128 v[172:175], v150 offset:1024
	ds_read_b128 v[176:179], v150 offset:2048
	ds_read_b128 v[184:187], v150 offset:3072
	s_add_u32 s24, s22, 0xfffc0080
	s_addc_u32 s25, s23, -1
	s_cmp_eq_u32 s51, 12
	s_cselect_b32 s27, s15, s25
	s_cselect_b32 s26, s47, s24
	s_cselect_b32 s25, s13, s50
	s_cselect_b32 s24, s48, s49
	v_lshl_add_u64 v[144:145], s[22:23], 0, v[136:137]
	s_add_i32 m0, s21, 0xc000
	ds_read_b128 v[188:191], v151
	ds_read_b128 v[192:195], v151 offset:1024
	ds_read_b128 v[196:199], v151 offset:2048
	ds_read_b128 v[200:203], v151 offset:3072
	ds_read_b128 v[204:207], v151 offset:4096
	ds_read_b128 v[208:211], v151 offset:5120
	ds_read_b128 v[212:215], v151 offset:6144
	ds_read_b128 v[216:219], v151 offset:7168
	global_load_lds_dwordx4 v[144:145], off
	v_lshl_add_u64 v[144:145], s[22:23], 0, v[138:139]
	s_add_i32 m0, s21, 0xe000
	s_nop 0
	global_load_lds_dwordx4 v[144:145], off
	s_cmp_eq_u32 s88, 1
	s_cbranch_scc1 .Lgw_1a
	s_waitcnt vmcnt(8)
.Lgw_1a:
	s_waitcnt vmcnt(16)
	s_waitcnt lgkmcnt(0)
	s_barrier
	s_setprio 1
	s_waitcnt lgkmcnt(0)
	v_mfma_f32_16x16x32_bf16 v[124:127], v[152:155], v[188:191], v[124:127]
	v_mfma_f32_16x16x32_bf16 v[120:123], v[160:163], v[188:191], v[120:123]
	v_mfma_f32_16x16x32_bf16 v[108:111], v[152:155], v[196:199], v[108:111]
	v_mfma_f32_16x16x32_bf16 v[104:107], v[160:163], v[196:199], v[104:107]
	v_mfma_f32_16x16x32_bf16 v[92:95], v[152:155], v[204:207], v[92:95]
	v_mfma_f32_16x16x32_bf16 v[88:91], v[160:163], v[204:207], v[88:91]
	v_mfma_f32_16x16x32_bf16 v[76:79], v[152:155], v[212:215], v[76:79]
	v_mfma_f32_16x16x32_bf16 v[72:75], v[160:163], v[212:215], v[72:75]
	v_mfma_f32_16x16x32_bf16 v[124:127], v[156:159], v[192:195], v[124:127]
	v_mfma_f32_16x16x32_bf16 v[120:123], v[164:167], v[192:195], v[120:123]
	v_mfma_f32_16x16x32_bf16 v[108:111], v[156:159], v[200:203], v[108:111]
	v_mfma_f32_16x16x32_bf16 v[104:107], v[164:167], v[200:203], v[104:107]
	v_mfma_f32_16x16x32_bf16 v[92:95], v[156:159], v[208:211], v[92:95]
	v_mfma_f32_16x16x32_bf16 v[88:91], v[164:167], v[208:211], v[88:91]
	v_mfma_f32_16x16x32_bf16 v[76:79], v[156:159], v[216:219], v[76:79]
	v_mfma_f32_16x16x32_bf16 v[72:75], v[164:167], v[216:219], v[72:75]
	s_setprio 0
	s_setprio 1
	v_mfma_f32_16x16x32_bf16 v[116:119], v[168:171], v[188:191], v[116:119]
	v_mfma_f32_16x16x32_bf16 v[112:115], v[176:179], v[188:191], v[112:115]
	v_mfma_f32_16x16x32_bf16 v[100:103], v[168:171], v[196:199], v[100:103]
	v_mfma_f32_16x16x32_bf16 v[96:99], v[176:179], v[196:199], v[96:99]
	v_mfma_f32_16x16x32_bf16 v[84:87], v[168:171], v[204:207], v[84:87]
	v_mfma_f32_16x16x32_bf16 v[80:83], v[176:179], v[204:207], v[80:83]
	v_mfma_f32_16x16x32_bf16 v[68:71], v[168:171], v[212:215], v[68:71]
	v_mfma_f32_16x16x32_bf16 v[64:67], v[176:179], v[212:215], v[64:67]
	v_mfma_f32_16x16x32_bf16 v[116:119], v[172:175], v[192:195], v[116:119]
	v_mfma_f32_16x16x32_bf16 v[112:115], v[184:187], v[192:195], v[112:115]
	v_mfma_f32_16x16x32_bf16 v[100:103], v[172:175], v[200:203], v[100:103]
	v_mfma_f32_16x16x32_bf16 v[96:99], v[184:187], v[200:203], v[96:99]
	v_mfma_f32_16x16x32_bf16 v[84:87], v[172:175], v[208:211], v[84:87]
	v_mfma_f32_16x16x32_bf16 v[80:83], v[184:187], v[208:211], v[80:83]
	v_mfma_f32_16x16x32_bf16 v[68:71], v[172:175], v[216:219], v[68:71]
	v_mfma_f32_16x16x32_bf16 v[64:67], v[184:187], v[216:219], v[64:67]
	s_setprio 0
	s_barrier
	s_add_i32 s52, s43, s34
	v_lshl_add_u64 v[144:145], s[24:25], 0, v[130:131]
	s_mov_b32 m0, s52
	ds_read_b128 v[188:191], v151 offset:16384
	ds_read_b128 v[192:195], v151 offset:17408
	ds_read_b128 v[196:199], v151 offset:18432
	ds_read_b128 v[200:203], v151 offset:19456
	ds_read_b128 v[204:207], v151 offset:20480
	ds_read_b128 v[208:211], v151 offset:21504
	ds_read_b128 v[212:215], v151 offset:22528
	ds_read_b128 v[216:219], v151 offset:23552
	global_load_lds_dwordx4 v[144:145], off
	s_add_i32 m0, s52, 0x2000
	s_add_u32 s52, s24, 0x40000
	v_lshl_add_u64 v[180:181], s[24:25], 0, v[134:135]
	s_addc_u32 s53, s25, 0
	s_add_i32 s54, s44, s34
	global_load_lds_dwordx4 v[180:181], off
	v_lshl_add_u64 v[220:221], s[52:53], 0, v[130:131]
	s_mov_b32 m0, s54
	v_lshl_add_u64 v[222:223], s[26:27], 0, v[132:133]
	global_load_lds_dwordx4 v[220:221], off
	v_lshl_add_u64 v[220:221], s[52:53], 0, v[134:135]
	s_add_i32 m0, s54, 0x2000
	s_nop 0
	global_load_lds_dwordx4 v[220:221], off
	v_lshl_add_u64 v[220:221], s[26:27], 0, v[128:129]
	s_mov_b32 m0, s21
	s_nop 0
	global_load_lds_dwordx4 v[220:221], off
	s_mov_b32 m0, s36
	s_nop 0
	global_load_lds_dwordx4 v[222:223], off
	s_cmp_eq_u32 s88, 1
	s_cbranch_scc1 .Lgw_1b
	s_waitcnt vmcnt(8)
.Lgw_1b:
	s_waitcnt vmcnt(16)
	s_waitcnt lgkmcnt(0)
	s_barrier
	s_mov_b32 s88, 0
	s_setprio 1
	s_waitcnt lgkmcnt(0)
	v_mfma_f32_16x16x32_bf16 v[60:63], v[152:155], v[188:191], v[60:63]
	v_mfma_f32_16x16x32_bf16 v[56:59], v[160:163], v[188:191], v[56:59]
	v_mfma_f32_16x16x32_bf16 v[44:47], v[152:155], v[196:199], v[44:47]
	v_mfma_f32_16x16x32_bf16 v[40:43], v[160:163], v[196:199], v[40:43]
	v_mfma_f32_16x16x32_bf16 v[28:31], v[152:155], v[204:207], v[28:31]
	v_mfma_f32_16x16x32_bf16 v[24:27], v[160:163], v[204:207], v[24:27]
	v_mfma_f32_16x16x32_bf16 v[12:15], v[152:155], v[212:215], v[12:15]
	v_mfma_f32_16x16x32_bf16 v[8:11], v[160:163], v[212:215], v[8:11]
	v_mfma_f32_16x16x32_bf16 v[60:63], v[156:159], v[192:195], v[60:63]
	v_mfma_f32_16x16x32_bf16 v[56:59], v[164:167], v[192:195], v[56:59]
	v_mfma_f32_16x16x32_bf16 v[44:47], v[156:159], v[200:203], v[44:47]
	v_mfma_f32_16x16x32_bf16 v[40:43], v[164:167], v[200:203], v[40:43]
	v_mfma_f32_16x16x32_bf16 v[28:31], v[156:159], v[208:211], v[28:31]
	v_mfma_f32_16x16x32_bf16 v[24:27], v[164:167], v[208:211], v[24:27]
	v_mfma_f32_16x16x32_bf16 v[12:15], v[156:159], v[216:219], v[12:15]
	v_mfma_f32_16x16x32_bf16 v[8:11], v[164:167], v[216:219], v[8:11]
	s_setprio 0
	s_setprio 1
	v_mfma_f32_16x16x32_bf16 v[52:55], v[168:171], v[188:191], v[52:55]
	v_mfma_f32_16x16x32_bf16 v[48:51], v[176:179], v[188:191], v[48:51]
	v_mfma_f32_16x16x32_bf16 v[36:39], v[168:171], v[196:199], v[36:39]
	v_mfma_f32_16x16x32_bf16 v[32:35], v[176:179], v[196:199], v[32:35]
	v_mfma_f32_16x16x32_bf16 v[20:23], v[168:171], v[204:207], v[20:23]
	v_mfma_f32_16x16x32_bf16 v[16:19], v[176:179], v[204:207], v[16:19]
	v_mfma_f32_16x16x32_bf16 v[4:7], v[168:171], v[212:215], v[4:7]
	v_mfma_f32_16x16x32_bf16 v[0:3], v[176:179], v[212:215], v[0:3]
	v_mfma_f32_16x16x32_bf16 v[52:55], v[172:175], v[192:195], v[52:55]
	v_mfma_f32_16x16x32_bf16 v[48:51], v[184:187], v[192:195], v[48:51]
	v_mfma_f32_16x16x32_bf16 v[36:39], v[172:175], v[200:203], v[36:39]
	v_mfma_f32_16x16x32_bf16 v[32:35], v[184:187], v[200:203], v[32:35]
	v_mfma_f32_16x16x32_bf16 v[20:23], v[172:175], v[208:211], v[20:23]
	v_mfma_f32_16x16x32_bf16 v[16:19], v[184:187], v[208:211], v[16:19]
	v_mfma_f32_16x16x32_bf16 v[4:7], v[172:175], v[216:219], v[4:7]
	v_mfma_f32_16x16x32_bf16 v[0:3], v[184:187], v[216:219], v[0:3]
	s_setprio 0
	s_barrier
	s_add_i32 s52, 0, 0x18000
	s_add_i32 s53, 0, 0x1c000
	v_add_u32_e32 v164, s52, v147
	v_add_u32_e32 v183, s53, v147
	ds_read_b128 v[152:155], v164
	ds_read_b128 v[156:159], v164 offset:1024
	ds_read_b128 v[160:163], v164 offset:2048
	ds_read_b128 v[164:167], v164 offset:3072
	ds_read_b128 v[168:171], v183
	ds_read_b128 v[172:175], v183 offset:1024
	ds_read_b128 v[176:179], v183 offset:2048
	ds_read_b128 v[184:187], v183 offset:3072
	s_add_u32 s26, s26, 0x40000
	s_addc_u32 s27, s27, 0
	s_mov_b32 m0, s37
	v_lshl_add_u64 v[224:225], s[26:27], 0, v[128:129]
	ds_read_b128 v[188:191], v151 offset:32768
	ds_read_b128 v[192:195], v151 offset:33792
	ds_read_b128 v[196:199], v151 offset:34816
	ds_read_b128 v[200:203], v151 offset:35840
	ds_read_b128 v[204:207], v151 offset:36864
	ds_read_b128 v[208:211], v151 offset:37888
	ds_read_b128 v[212:215], v151 offset:38912
	ds_read_b128 v[216:219], v151 offset:39936
	global_load_lds_dwordx4 v[224:225], off
	v_lshl_add_u64 v[224:225], s[26:27], 0, v[132:133]
	s_mov_b32 m0, s38
	s_nop 0
	global_load_lds_dwordx4 v[224:225], off
	s_waitcnt vmcnt(8)
	s_waitcnt lgkmcnt(0)
	s_barrier
	s_setprio 1
	s_waitcnt lgkmcnt(0)
	v_mfma_f32_16x16x32_bf16 v[124:127], v[152:155], v[188:191], v[124:127]
	v_mfma_f32_16x16x32_bf16 v[120:123], v[160:163], v[188:191], v[120:123]
	v_mfma_f32_16x16x32_bf16 v[108:111], v[152:155], v[196:199], v[108:111]
	v_mfma_f32_16x16x32_bf16 v[104:107], v[160:163], v[196:199], v[104:107]
	v_mfma_f32_16x16x32_bf16 v[92:95], v[152:155], v[204:207], v[92:95]
	v_mfma_f32_16x16x32_bf16 v[88:91], v[160:163], v[204:207], v[88:91]
	v_mfma_f32_16x16x32_bf16 v[76:79], v[152:155], v[212:215], v[76:79]
	v_mfma_f32_16x16x32_bf16 v[72:75], v[160:163], v[212:215], v[72:75]
	v_mfma_f32_16x16x32_bf16 v[124:127], v[156:159], v[192:195], v[124:127]
	v_mfma_f32_16x16x32_bf16 v[120:123], v[164:167], v[192:195], v[120:123]
	v_mfma_f32_16x16x32_bf16 v[108:111], v[156:159], v[200:203], v[108:111]
	v_mfma_f32_16x16x32_bf16 v[104:107], v[164:167], v[200:203], v[104:107]
	v_mfma_f32_16x16x32_bf16 v[92:95], v[156:159], v[208:211], v[92:95]
	v_mfma_f32_16x16x32_bf16 v[88:91], v[164:167], v[208:211], v[88:91]
	v_mfma_f32_16x16x32_bf16 v[76:79], v[156:159], v[216:219], v[76:79]
	v_mfma_f32_16x16x32_bf16 v[72:75], v[164:167], v[216:219], v[72:75]
	s_setprio 0
	s_setprio 1
	v_mfma_f32_16x16x32_bf16 v[116:119], v[168:171], v[188:191], v[116:119]
	v_mfma_f32_16x16x32_bf16 v[112:115], v[176:179], v[188:191], v[112:115]
	v_mfma_f32_16x16x32_bf16 v[100:103], v[168:171], v[196:199], v[100:103]
	v_mfma_f32_16x16x32_bf16 v[96:99], v[176:179], v[196:199], v[96:99]
	v_mfma_f32_16x16x32_bf16 v[84:87], v[168:171], v[204:207], v[84:87]
	v_mfma_f32_16x16x32_bf16 v[80:83], v[176:179], v[204:207], v[80:83]
	v_mfma_f32_16x16x32_bf16 v[68:71], v[168:171], v[212:215], v[68:71]
	v_mfma_f32_16x16x32_bf16 v[64:67], v[176:179], v[212:215], v[64:67]
	v_mfma_f32_16x16x32_bf16 v[116:119], v[172:175], v[192:195], v[116:119]
	v_mfma_f32_16x16x32_bf16 v[112:115], v[184:187], v[192:195], v[112:115]
	v_mfma_f32_16x16x32_bf16 v[100:103], v[172:175], v[200:203], v[100:103]
	v_mfma_f32_16x16x32_bf16 v[96:99], v[184:187], v[200:203], v[96:99]
	v_mfma_f32_16x16x32_bf16 v[84:87], v[172:175], v[208:211], v[84:87]
	v_mfma_f32_16x16x32_bf16 v[80:83], v[184:187], v[208:211], v[80:83]
	v_mfma_f32_16x16x32_bf16 v[68:71], v[172:175], v[216:219], v[68:71]
	v_mfma_f32_16x16x32_bf16 v[64:67], v[184:187], v[216:219], v[64:67]
	s_setprio 0
	s_barrier
	s_add_i32 s26, s52, s34
	v_lshl_add_u64 v[144:145], v[144:145], 0, s[8:9]
	s_mov_b32 m0, s26
	ds_read_b128 v[188:191], v151 offset:49152
	ds_read_b128 v[192:195], v151 offset:50176
	ds_read_b128 v[196:199], v151 offset:51200
	ds_read_b128 v[200:203], v151 offset:52224
	ds_read_b128 v[204:207], v151 offset:53248
	ds_read_b128 v[208:211], v151 offset:54272
	ds_read_b128 v[212:215], v151 offset:55296
	ds_read_b128 v[216:219], v151 offset:56320
	global_load_lds_dwordx4 v[144:145], off
	s_add_i32 m0, s26, 0x2000
	s_add_u32 s24, s24, 0x40080
	v_lshl_add_u64 v[144:145], v[180:181], 0, s[8:9]
	s_addc_u32 s25, s25, 0
	s_add_i32 s26, s53, s34
	global_load_lds_dwordx4 v[144:145], off
	v_lshl_add_u64 v[144:145], s[24:25], 0, v[130:131]
	s_mov_b32 m0, s26
	s_nop 0
	global_load_lds_dwordx4 v[144:145], off
	v_lshl_add_u64 v[144:145], s[24:25], 0, v[134:135]
	s_add_i32 m0, s26, 0x2000
	s_nop 0
	global_load_lds_dwordx4 v[144:145], off
	v_lshl_add_u64 v[144:145], v[220:221], 0, s[8:9]
	s_mov_b32 m0, s41
	s_nop 0
	global_load_lds_dwordx4 v[144:145], off
	v_lshl_add_u64 v[144:145], v[222:223], 0, s[8:9]
	s_mov_b32 m0, s42
	s_nop 0
	global_load_lds_dwordx4 v[144:145], off
	s_waitcnt vmcnt(8)
	s_waitcnt lgkmcnt(0)
	s_barrier
	s_setprio 1
	s_waitcnt lgkmcnt(0)
	v_mfma_f32_16x16x32_bf16 v[60:63], v[152:155], v[188:191], v[60:63]
	v_mfma_f32_16x16x32_bf16 v[56:59], v[160:163], v[188:191], v[56:59]
	v_mfma_f32_16x16x32_bf16 v[44:47], v[152:155], v[196:199], v[44:47]
	v_mfma_f32_16x16x32_bf16 v[40:43], v[160:163], v[196:199], v[40:43]
	v_mfma_f32_16x16x32_bf16 v[28:31], v[152:155], v[204:207], v[28:31]
	v_mfma_f32_16x16x32_bf16 v[24:27], v[160:163], v[204:207], v[24:27]
	v_mfma_f32_16x16x32_bf16 v[12:15], v[152:155], v[212:215], v[12:15]
	v_mfma_f32_16x16x32_bf16 v[8:11], v[160:163], v[212:215], v[8:11]
	v_mfma_f32_16x16x32_bf16 v[60:63], v[156:159], v[192:195], v[60:63]
	v_mfma_f32_16x16x32_bf16 v[56:59], v[164:167], v[192:195], v[56:59]
	v_mfma_f32_16x16x32_bf16 v[44:47], v[156:159], v[200:203], v[44:47]
	v_mfma_f32_16x16x32_bf16 v[40:43], v[164:167], v[200:203], v[40:43]
	v_mfma_f32_16x16x32_bf16 v[28:31], v[156:159], v[208:211], v[28:31]
	v_mfma_f32_16x16x32_bf16 v[24:27], v[164:167], v[208:211], v[24:27]
	v_mfma_f32_16x16x32_bf16 v[12:15], v[156:159], v[216:219], v[12:15]
	v_mfma_f32_16x16x32_bf16 v[8:11], v[164:167], v[216:219], v[8:11]
	s_setprio 0
	s_setprio 1
	v_mfma_f32_16x16x32_bf16 v[52:55], v[168:171], v[188:191], v[52:55]
	v_mfma_f32_16x16x32_bf16 v[48:51], v[176:179], v[188:191], v[48:51]
	v_mfma_f32_16x16x32_bf16 v[36:39], v[168:171], v[196:199], v[36:39]
	v_mfma_f32_16x16x32_bf16 v[32:35], v[176:179], v[196:199], v[32:35]
	v_mfma_f32_16x16x32_bf16 v[20:23], v[168:171], v[204:207], v[20:23]
	v_mfma_f32_16x16x32_bf16 v[16:19], v[176:179], v[204:207], v[16:19]
	v_mfma_f32_16x16x32_bf16 v[4:7], v[168:171], v[212:215], v[4:7]
	v_mfma_f32_16x16x32_bf16 v[0:3], v[176:179], v[212:215], v[0:3]
	v_mfma_f32_16x16x32_bf16 v[52:55], v[172:175], v[192:195], v[52:55]
	v_mfma_f32_16x16x32_bf16 v[48:51], v[184:187], v[192:195], v[48:51]
	v_mfma_f32_16x16x32_bf16 v[36:39], v[172:175], v[200:203], v[36:39]
	v_mfma_f32_16x16x32_bf16 v[32:35], v[184:187], v[200:203], v[32:35]
	v_mfma_f32_16x16x32_bf16 v[20:23], v[172:175], v[208:211], v[20:23]
	v_mfma_f32_16x16x32_bf16 v[16:19], v[184:187], v[208:211], v[16:19]
	v_mfma_f32_16x16x32_bf16 v[4:7], v[172:175], v[216:219], v[4:7]
	v_mfma_f32_16x16x32_bf16 v[0:3], v[184:187], v[216:219], v[0:3]
	s_setprio 0
	s_barrier
	s_add_i32 s51, s51, 2
	s_add_u32 s22, s22, 0x100
	s_addc_u32 s23, s23, 0
	s_add_u32 s49, s49, 0x100
	s_addc_u32 s50, s50, 0
	s_cmp_gt_u32 s51, 13
	s_cbranch_scc0 .LBB0_259
	s_and_b64 vcc, exec, s[10:11]
	s_cbranch_vccz .LBB0_262
	s_barrier

.LBB0_324:
	s_add_u32 s8, s84, 0xc000000
	s_addc_u32 s9, s85, 0
	s_lshl_b32 s5, s5, 5
	s_mov_b64 s[10:11], 0x80
	s_and_b32 s5, s5, 0x60
	s_add_i32 m0, s37, 0x18000
	v_lshl_add_u64 v[6:7], v[6:7], 0, s[10:11]
	s_ashr_i32 s42, s82, 31
	s_lshl_b32 s14, s1, 13
	s_lshl_b32 s15, s5, 7
	s_waitcnt vmcnt(2)
	s_barrier
	global_load_lds_dwordx4 v[6:7], off
	v_lshl_add_u64 v[4:5], v[4:5], 0, s[10:11]
	s_add_i32 m0, s37, 0x1a000
	s_add_i32 s43, s37, 0x8000
	s_add_i32 s44, s37, 0xa000
	global_load_lds_dwordx4 v[4:5], off
	v_lshl_add_u64 v[0:1], v[0:1], 0, s[10:11]
	s_mov_b32 m0, s43
	s_add_u32 s12, s26, 0xb0080
	global_load_lds_dwordx4 v[0:1], off
	v_lshl_add_u64 v[0:1], v[2:3], 0, s[10:11]
	s_mov_b32 m0, s44
	s_addc_u32 s13, s27, 0
	global_load_lds_dwordx4 v[0:1], off
	s_add_i32 m0, s37, 0x1c000
	v_lshl_add_u64 v[0:1], s[12:13], 0, v[130:131]
	global_load_lds_dwordx4 v[0:1], off
	v_lshl_add_u64 v[0:1], s[12:13], 0, v[134:135]
	s_add_i32 m0, s37, 0x1e000
	s_sext_i32_i8 s54, s4
	global_load_lds_dwordx4 v[0:1], off
	v_and_b32_e32 v0, 15, v182
	v_lshlrev_b32_e32 v1, 1, v10
	v_lshlrev_b32_e32 v2, 6, v182
	s_movk_i32 s4, 0x3c0
	v_lshlrev_b32_e32 v3, 2, v182
	v_and_or_b32 v2, v2, s4, v1
	v_and_b32_e32 v3, 32, v3
	v_lshl_or_b32 v144, s1, 6, v0
	v_lshl_or_b32 v0, v0, 6, v1
	s_waitcnt vmcnt(6)
	s_cmpk_lt_u32 s0, 0x100
	v_add_u16_e32 v1, v8, v9
	v_bitop3_b32 v0, v0, s14, v3 bitop3:0xde
	v_bitop3_b32 v145, s15, v2, v3 bitop3:0xf6
	s_cselect_b64 s[12:13], -1, 0
	v_lshrrev_b16_e32 v1, 1, v1
	s_add_i32 s45, 0, 0x10000
	s_add_i32 s46, 0, 0x14000
	v_or_b32_e32 v146, s5, v10
	v_add_lshl_u32 v136, v11, v1, 1
	v_mov_b32_e32 v137, v131
	v_add_lshl_u32 v138, v12, v1, 1
	v_mov_b32_e32 v139, v131
	v_mov_b64_e32 v[140:141], 0x400
	v_mov_b64_e32 v[142:143], 0x3ff
	v_add_u32_e32 v147, s45, v145
	v_add_u32_e32 v148, s46, v145
	v_add_u32_e32 v149, 0, v0
	s_mov_b64 s[14:15], 0x40000
	s_mov_b32 s47, 0x40000
	s_mov_b64 s[16:17], 0x48000
	s_mov_b32 s48, 0x48000
	s_mov_b64 s[18:19], 0x50000
	s_mov_b32 s49, 0x50000
	s_mov_b64 s[20:21], 0x58000
	s_mov_b32 s50, 0x58000
	s_barrier
	s_mov_b32 s88, 0
	s_branch .LBB0_327

.LBB0_326:
	s_mov_b32 s88, 1
	s_andn2_b64 vcc, exec, s[0:1]
	s_mov_b32 s54, s52
	s_mov_b32 s51, s53
	s_mov_b64 s[26:27], s[22:23]
	s_mov_b64 s[24:25], s[4:5]
	s_cbranch_vccz .LBB0_344

.LBB0_338:
	ds_read_b128 v[150:153], v147
	ds_read_b128 v[154:157], v147 offset:1024
	ds_read_b128 v[158:161], v147 offset:2048
	ds_read_b128 v[162:165], v147 offset:3072
	ds_read_b128 v[166:169], v148
	ds_read_b128 v[170:173], v148 offset:1024
	ds_read_b128 v[174:177], v148 offset:2048
	ds_read_b128 v[178:181], v148 offset:3072
	s_add_u32 s26, s24, 0xfff50080
	s_addc_u32 s27, s25, -1
	s_cmp_eq_u32 s57, 40
	s_cselect_b32 s29, s5, s27
	s_cselect_b32 s28, s4, s26
	s_cselect_b32 s27, s23, s56
	s_cselect_b32 s26, s22, s55
	v_lshl_add_u64 v[216:217], s[24:25], 0, v[136:137]
	s_add_i32 m0, s37, 0xc000
	ds_read_b128 v[184:187], v149
	ds_read_b128 v[188:191], v149 offset:1024
	ds_read_b128 v[192:195], v149 offset:2048
	ds_read_b128 v[196:199], v149 offset:3072
	ds_read_b128 v[200:203], v149 offset:4096
	ds_read_b128 v[204:207], v149 offset:5120
	ds_read_b128 v[208:211], v149 offset:6144
	ds_read_b128 v[212:215], v149 offset:7168
	global_load_lds_dwordx4 v[216:217], off
	v_lshl_add_u64 v[216:217], s[24:25], 0, v[138:139]
	s_add_i32 m0, s37, 0xe000
	s_nop 0
	global_load_lds_dwordx4 v[216:217], off
	s_cmp_eq_u32 s88, 1
	s_cbranch_scc1 .Lgw_2a
	s_waitcnt vmcnt(8)
.Lgw_2a:
	s_waitcnt vmcnt(24)
	s_waitcnt lgkmcnt(0)
	s_barrier
	s_setprio 1
	s_waitcnt lgkmcnt(0)
	v_mfma_f32_16x16x32_bf16 v[124:127], v[150:153], v[184:187], v[124:127]
	v_mfma_f32_16x16x32_bf16 v[120:123], v[158:161], v[184:187], v[120:123]
	v_mfma_f32_16x16x32_bf16 v[116:119], v[150:153], v[192:195], v[116:119]
	v_mfma_f32_16x16x32_bf16 v[112:115], v[158:161], v[192:195], v[112:115]
	v_mfma_f32_16x16x32_bf16 v[100:103], v[150:153], v[200:203], v[100:103]
	v_mfma_f32_16x16x32_bf16 v[96:99], v[158:161], v[200:203], v[96:99]
	v_mfma_f32_16x16x32_bf16 v[84:87], v[150:153], v[208:211], v[84:87]
	v_mfma_f32_16x16x32_bf16 v[80:83], v[158:161], v[208:211], v[80:83]
	v_mfma_f32_16x16x32_bf16 v[124:127], v[154:157], v[188:191], v[124:127]
	v_mfma_f32_16x16x32_bf16 v[120:123], v[162:165], v[188:191], v[120:123]
	v_mfma_f32_16x16x32_bf16 v[116:119], v[154:157], v[196:199], v[116:119]
	v_mfma_f32_16x16x32_bf16 v[112:115], v[162:165], v[196:199], v[112:115]
	v_mfma_f32_16x16x32_bf16 v[100:103], v[154:157], v[204:207], v[100:103]
	v_mfma_f32_16x16x32_bf16 v[96:99], v[162:165], v[204:207], v[96:99]
	v_mfma_f32_16x16x32_bf16 v[84:87], v[154:157], v[212:215], v[84:87]
	v_mfma_f32_16x16x32_bf16 v[80:83], v[162:165], v[212:215], v[80:83]
	s_setprio 0
	s_setprio 1
	v_mfma_f32_16x16x32_bf16 v[108:111], v[166:169], v[184:187], v[108:111]
	v_mfma_f32_16x16x32_bf16 v[104:107], v[174:177], v[184:187], v[104:107]
	v_mfma_f32_16x16x32_bf16 v[92:95], v[166:169], v[192:195], v[92:95]
	v_mfma_f32_16x16x32_bf16 v[88:91], v[174:177], v[192:195], v[88:91]
	v_mfma_f32_16x16x32_bf16 v[76:79], v[166:169], v[200:203], v[76:79]
	v_mfma_f32_16x16x32_bf16 v[72:75], v[174:177], v[200:203], v[72:75]
	v_mfma_f32_16x16x32_bf16 v[68:71], v[166:169], v[208:211], v[68:71]
	v_mfma_f32_16x16x32_bf16 v[64:67], v[174:177], v[208:211], v[64:67]
	v_mfma_f32_16x16x32_bf16 v[108:111], v[170:173], v[188:191], v[108:111]
	v_mfma_f32_16x16x32_bf16 v[104:107], v[178:181], v[188:191], v[104:107]
	v_mfma_f32_16x16x32_bf16 v[92:95], v[170:173], v[196:199], v[92:95]
	v_mfma_f32_16x16x32_bf16 v[88:91], v[178:181], v[196:199], v[88:91]
	v_mfma_f32_16x16x32_bf16 v[76:79], v[170:173], v[204:207], v[76:79]
	v_mfma_f32_16x16x32_bf16 v[72:75], v[178:181], v[204:207], v[72:75]
	v_mfma_f32_16x16x32_bf16 v[68:71], v[170:173], v[212:215], v[68:71]
	v_mfma_f32_16x16x32_bf16 v[64:67], v[178:181], v[212:215], v[64:67]
	s_setprio 0
	s_barrier
	s_add_i32 s58, s45, s36
	v_lshl_add_u64 v[216:217], s[26:27], 0, v[130:131]
	s_mov_b32 m0, s58
	ds_read_b128 v[184:187], v149 offset:16384
	ds_read_b128 v[188:191], v149 offset:17408
	ds_read_b128 v[192:195], v149 offset:18432
	ds_read_b128 v[196:199], v149 offset:19456
	ds_read_b128 v[200:203], v149 offset:20480
	ds_read_b128 v[204:207], v149 offset:21504
	ds_read_b128 v[208:211], v149 offset:22528
	ds_read_b128 v[212:215], v149 offset:23552
	global_load_lds_dwordx4 v[216:217], off
	s_add_i32 m0, s58, 0x2000
	s_add_u32 s58, s26, 0xb0000
	v_lshl_add_u64 v[218:219], s[26:27], 0, v[134:135]
	s_addc_u32 s59, s27, 0
	s_add_i32 s60, s46, s36
	global_load_lds_dwordx4 v[218:219], off
	v_lshl_add_u64 v[220:221], s[58:59], 0, v[130:131]
	s_mov_b32 m0, s60
	v_lshl_add_u64 v[222:223], s[28:29], 0, v[132:133]
	global_load_lds_dwordx4 v[220:221], off
	v_lshl_add_u64 v[220:221], s[58:59], 0, v[134:135]
	s_add_i32 m0, s60, 0x2000
	s_nop 0
	global_load_lds_dwordx4 v[220:221], off
	v_lshl_add_u64 v[220:221], s[28:29], 0, v[128:129]
	s_mov_b32 m0, s37
	s_nop 0
	global_load_lds_dwordx4 v[220:221], off
	s_mov_b32 m0, s38
	s_nop 0
	global_load_lds_dwordx4 v[222:223], off
	s_cmp_eq_u32 s88, 1
	s_cbranch_scc1 .Lgw_2b
	s_waitcnt vmcnt(8)
.Lgw_2b:
	s_waitcnt vmcnt(24)
	s_waitcnt lgkmcnt(0)
	s_barrier
	s_mov_b32 s88, 0
	s_setprio 1
	s_waitcnt lgkmcnt(0)
	v_mfma_f32_16x16x32_bf16 v[60:63], v[150:153], v[184:187], v[60:63]
	v_mfma_f32_16x16x32_bf16 v[56:59], v[158:161], v[184:187], v[56:59]
	v_mfma_f32_16x16x32_bf16 v[52:55], v[150:153], v[192:195], v[52:55]
	v_mfma_f32_16x16x32_bf16 v[48:51], v[158:161], v[192:195], v[48:51]
	v_mfma_f32_16x16x32_bf16 v[36:39], v[150:153], v[200:203], v[36:39]
	v_mfma_f32_16x16x32_bf16 v[32:35], v[158:161], v[200:203], v[32:35]
	v_mfma_f32_16x16x32_bf16 v[20:23], v[150:153], v[208:211], v[20:23]
	v_mfma_f32_16x16x32_bf16 v[16:19], v[158:161], v[208:211], v[16:19]
	v_mfma_f32_16x16x32_bf16 v[60:63], v[154:157], v[188:191], v[60:63]
	v_mfma_f32_16x16x32_bf16 v[56:59], v[162:165], v[188:191], v[56:59]
	v_mfma_f32_16x16x32_bf16 v[52:55], v[154:157], v[196:199], v[52:55]
	v_mfma_f32_16x16x32_bf16 v[48:51], v[162:165], v[196:199], v[48:51]
	v_mfma_f32_16x16x32_bf16 v[36:39], v[154:157], v[204:207], v[36:39]
	v_mfma_f32_16x16x32_bf16 v[32:35], v[162:165], v[204:207], v[32:35]
	v_mfma_f32_16x16x32_bf16 v[20:23], v[154:157], v[212:215], v[20:23]
	v_mfma_f32_16x16x32_bf16 v[16:19], v[162:165], v[212:215], v[16:19]
	s_setprio 0
	s_setprio 1
	v_mfma_f32_16x16x32_bf16 v[44:47], v[166:169], v[184:187], v[44:47]
	v_mfma_f32_16x16x32_bf16 v[40:43], v[174:177], v[184:187], v[40:43]
	v_mfma_f32_16x16x32_bf16 v[28:31], v[166:169], v[192:195], v[28:31]
	v_mfma_f32_16x16x32_bf16 v[24:27], v[174:177], v[192:195], v[24:27]
	v_mfma_f32_16x16x32_bf16 v[12:15], v[166:169], v[200:203], v[12:15]
	v_mfma_f32_16x16x32_bf16 v[8:11], v[174:177], v[200:203], v[8:11]
	v_mfma_f32_16x16x32_bf16 v[4:7], v[166:169], v[208:211], v[4:7]
	v_mfma_f32_16x16x32_bf16 v[0:3], v[174:177], v[208:211], v[0:3]
	v_mfma_f32_16x16x32_bf16 v[44:47], v[170:173], v[188:191], v[44:47]
	v_mfma_f32_16x16x32_bf16 v[40:43], v[178:181], v[188:191], v[40:43]
	v_mfma_f32_16x16x32_bf16 v[28:31], v[170:173], v[196:199], v[28:31]
	v_mfma_f32_16x16x32_bf16 v[24:27], v[178:181], v[196:199], v[24:27]
	v_mfma_f32_16x16x32_bf16 v[12:15], v[170:173], v[204:207], v[12:15]
	v_mfma_f32_16x16x32_bf16 v[8:11], v[178:181], v[204:207], v[8:11]
	v_mfma_f32_16x16x32_bf16 v[4:7], v[170:173], v[212:215], v[4:7]
	v_mfma_f32_16x16x32_bf16 v[0:3], v[178:181], v[212:215], v[0:3]
	s_setprio 0
	s_barrier
	s_add_i32 s58, 0, 0x18000
	s_add_i32 s59, 0, 0x1c000
	v_add_u32_e32 v162, s58, v145
	v_add_u32_e32 v178, s59, v145
	ds_read_b128 v[150:153], v162
	ds_read_b128 v[154:157], v162 offset:1024
	ds_read_b128 v[158:161], v162 offset:2048
	ds_read_b128 v[162:165], v162 offset:3072
	ds_read_b128 v[166:169], v178
	ds_read_b128 v[170:173], v178 offset:1024
	ds_read_b128 v[174:177], v178 offset:2048
	ds_read_b128 v[178:181], v178 offset:3072
	s_add_u32 s28, s28, 0xb0000
	s_addc_u32 s29, s29, 0
	s_mov_b32 m0, s39
	v_lshl_add_u64 v[224:225], s[28:29], 0, v[128:129]
	ds_read_b128 v[184:187], v149 offset:32768
	ds_read_b128 v[188:191], v149 offset:33792
	ds_read_b128 v[192:195], v149 offset:34816
	ds_read_b128 v[196:199], v149 offset:35840
	ds_read_b128 v[200:203], v149 offset:36864
	ds_read_b128 v[204:207], v149 offset:37888
	ds_read_b128 v[208:211], v149 offset:38912
	ds_read_b128 v[212:215], v149 offset:39936
	global_load_lds_dwordx4 v[224:225], off
	v_lshl_add_u64 v[224:225], s[28:29], 0, v[132:133]
	s_mov_b32 m0, s40
	s_nop 0
	global_load_lds_dwordx4 v[224:225], off
	s_waitcnt vmcnt(8)
	s_waitcnt lgkmcnt(0)
	s_barrier
	s_setprio 1
	s_waitcnt lgkmcnt(0)
	v_mfma_f32_16x16x32_bf16 v[124:127], v[150:153], v[184:187], v[124:127]
	v_mfma_f32_16x16x32_bf16 v[120:123], v[158:161], v[184:187], v[120:123]
	v_mfma_f32_16x16x32_bf16 v[116:119], v[150:153], v[192:195], v[116:119]
	v_mfma_f32_16x16x32_bf16 v[112:115], v[158:161], v[192:195], v[112:115]
	v_mfma_f32_16x16x32_bf16 v[100:103], v[150:153], v[200:203], v[100:103]
	v_mfma_f32_16x16x32_bf16 v[96:99], v[158:161], v[200:203], v[96:99]
	v_mfma_f32_16x16x32_bf16 v[84:87], v[150:153], v[208:211], v[84:87]
	v_mfma_f32_16x16x32_bf16 v[80:83], v[158:161], v[208:211], v[80:83]
	v_mfma_f32_16x16x32_bf16 v[124:127], v[154:157], v[188:191], v[124:127]
	v_mfma_f32_16x16x32_bf16 v[120:123], v[162:165], v[188:191], v[120:123]
	v_mfma_f32_16x16x32_bf16 v[116:119], v[154:157], v[196:199], v[116:119]
	v_mfma_f32_16x16x32_bf16 v[112:115], v[162:165], v[196:199], v[112:115]
	v_mfma_f32_16x16x32_bf16 v[100:103], v[154:157], v[204:207], v[100:103]
	v_mfma_f32_16x16x32_bf16 v[96:99], v[162:165], v[204:207], v[96:99]
	v_mfma_f32_16x16x32_bf16 v[84:87], v[154:157], v[212:215], v[84:87]
	v_mfma_f32_16x16x32_bf16 v[80:83], v[162:165], v[212:215], v[80:83]
	s_setprio 0
	s_setprio 1
	v_mfma_f32_16x16x32_bf16 v[108:111], v[166:169], v[184:187], v[108:111]
	v_mfma_f32_16x16x32_bf16 v[104:107], v[174:177], v[184:187], v[104:107]
	v_mfma_f32_16x16x32_bf16 v[92:95], v[166:169], v[192:195], v[92:95]
	v_mfma_f32_16x16x32_bf16 v[88:91], v[174:177], v[192:195], v[88:91]
	v_mfma_f32_16x16x32_bf16 v[76:79], v[166:169], v[200:203], v[76:79]
	v_mfma_f32_16x16x32_bf16 v[72:75], v[174:177], v[200:203], v[72:75]
	v_mfma_f32_16x16x32_bf16 v[68:71], v[166:169], v[208:211], v[68:71]
	v_mfma_f32_16x16x32_bf16 v[64:67], v[174:177], v[208:211], v[64:67]
	v_mfma_f32_16x16x32_bf16 v[108:111], v[170:173], v[188:191], v[108:111]
	v_mfma_f32_16x16x32_bf16 v[104:107], v[178:181], v[188:191], v[104:107]
	v_mfma_f32_16x16x32_bf16 v[92:95], v[170:173], v[196:199], v[92:95]
	v_mfma_f32_16x16x32_bf16 v[88:91], v[178:181], v[196:199], v[88:91]
	v_mfma_f32_16x16x32_bf16 v[76:79], v[170:173], v[204:207], v[76:79]
	v_mfma_f32_16x16x32_bf16 v[72:75], v[178:181], v[204:207], v[72:75]
	v_mfma_f32_16x16x32_bf16 v[68:71], v[170:173], v[212:215], v[68:71]
	v_mfma_f32_16x16x32_bf16 v[64:67], v[178:181], v[212:215], v[64:67]
	s_setprio 0
	s_barrier
	s_add_i32 s28, s58, s36
	v_lshl_add_u64 v[216:217], v[216:217], 0, s[10:11]
	s_mov_b32 m0, s28
	ds_read_b128 v[184:187], v149 offset:49152
	ds_read_b128 v[188:191], v149 offset:50176
	ds_read_b128 v[192:195], v149 offset:51200
	ds_read_b128 v[196:199], v149 offset:52224
	ds_read_b128 v[200:203], v149 offset:53248
	ds_read_b128 v[204:207], v149 offset:54272
	ds_read_b128 v[208:211], v149 offset:55296
	ds_read_b128 v[212:215], v149 offset:56320
	global_load_lds_dwordx4 v[216:217], off
	s_add_i32 m0, s28, 0x2000
	s_add_u32 s26, s26, 0xb0080
	v_lshl_add_u64 v[216:217], v[218:219], 0, s[10:11]
	s_addc_u32 s27, s27, 0
	s_add_i32 s28, s59, s36
	global_load_lds_dwordx4 v[216:217], off
	v_lshl_add_u64 v[216:217], s[26:27], 0, v[130:131]
	s_mov_b32 m0, s28
	s_nop 0
	global_load_lds_dwordx4 v[216:217], off
	v_lshl_add_u64 v[216:217], s[26:27], 0, v[134:135]
	s_add_i32 m0, s28, 0x2000
	s_nop 0
	global_load_lds_dwordx4 v[216:217], off
	v_lshl_add_u64 v[216:217], v[220:221], 0, s[10:11]
	s_mov_b32 m0, s43
	s_nop 0
	global_load_lds_dwordx4 v[216:217], off
	v_lshl_add_u64 v[216:217], v[222:223], 0, s[10:11]
	s_mov_b32 m0, s44
	s_nop 0
	global_load_lds_dwordx4 v[216:217], off
	s_waitcnt vmcnt(8)
	s_waitcnt lgkmcnt(0)
	s_barrier
	s_setprio 1
	s_waitcnt lgkmcnt(0)
	v_mfma_f32_16x16x32_bf16 v[60:63], v[150:153], v[184:187], v[60:63]
	v_mfma_f32_16x16x32_bf16 v[56:59], v[158:161], v[184:187], v[56:59]
	v_mfma_f32_16x16x32_bf16 v[52:55], v[150:153], v[192:195], v[52:55]
	v_mfma_f32_16x16x32_bf16 v[48:51], v[158:161], v[192:195], v[48:51]
	v_mfma_f32_16x16x32_bf16 v[36:39], v[150:153], v[200:203], v[36:39]
	v_mfma_f32_16x16x32_bf16 v[32:35], v[158:161], v[200:203], v[32:35]
	v_mfma_f32_16x16x32_bf16 v[20:23], v[150:153], v[208:211], v[20:23]
	v_mfma_f32_16x16x32_bf16 v[16:19], v[158:161], v[208:211], v[16:19]
	v_mfma_f32_16x16x32_bf16 v[60:63], v[154:157], v[188:191], v[60:63]
	v_mfma_f32_16x16x32_bf16 v[56:59], v[162:165], v[188:191], v[56:59]
	v_mfma_f32_16x16x32_bf16 v[52:55], v[154:157], v[196:199], v[52:55]
	v_mfma_f32_16x16x32_bf16 v[48:51], v[162:165], v[196:199], v[48:51]
	v_mfma_f32_16x16x32_bf16 v[36:39], v[154:157], v[204:207], v[36:39]
	v_mfma_f32_16x16x32_bf16 v[32:35], v[162:165], v[204:207], v[32:35]
	v_mfma_f32_16x16x32_bf16 v[20:23], v[154:157], v[212:215], v[20:23]
	v_mfma_f32_16x16x32_bf16 v[16:19], v[162:165], v[212:215], v[16:19]
	s_setprio 0
	s_setprio 1
	v_mfma_f32_16x16x32_bf16 v[44:47], v[166:169], v[184:187], v[44:47]
	v_mfma_f32_16x16x32_bf16 v[40:43], v[174:177], v[184:187], v[40:43]
	v_mfma_f32_16x16x32_bf16 v[28:31], v[166:169], v[192:195], v[28:31]
	v_mfma_f32_16x16x32_bf16 v[24:27], v[174:177], v[192:195], v[24:27]
	v_mfma_f32_16x16x32_bf16 v[12:15], v[166:169], v[200:203], v[12:15]
	v_mfma_f32_16x16x32_bf16 v[8:11], v[174:177], v[200:203], v[8:11]
	v_mfma_f32_16x16x32_bf16 v[4:7], v[166:169], v[208:211], v[4:7]
	v_mfma_f32_16x16x32_bf16 v[0:3], v[174:177], v[208:211], v[0:3]
	v_mfma_f32_16x16x32_bf16 v[44:47], v[170:173], v[188:191], v[44:47]
	v_mfma_f32_16x16x32_bf16 v[40:43], v[178:181], v[188:191], v[40:43]
	v_mfma_f32_16x16x32_bf16 v[28:31], v[170:173], v[196:199], v[28:31]
	v_mfma_f32_16x16x32_bf16 v[24:27], v[178:181], v[196:199], v[24:27]
	v_mfma_f32_16x16x32_bf16 v[12:15], v[170:173], v[204:207], v[12:15]
	v_mfma_f32_16x16x32_bf16 v[8:11], v[178:181], v[204:207], v[8:11]
	v_mfma_f32_16x16x32_bf16 v[4:7], v[170:173], v[212:215], v[4:7]
	v_mfma_f32_16x16x32_bf16 v[0:3], v[178:181], v[212:215], v[0:3]
	s_setprio 0
	s_barrier
	s_add_i32 s57, s57, 2
	s_add_u32 s24, s24, 0x100
	s_addc_u32 s25, s25, 0
	s_add_u32 s55, s55, 0x100
	s_addc_u32 s56, s56, 0
	s_cmp_gt_u32 s57, 41
	s_cbranch_scc0 .LBB0_338
	s_and_b64 vcc, exec, s[12:13]
	s_cbranch_vccz .LBB0_341
	s_barrier

.LBB0_469:
	s_add_u32 s10, s84, 0x14000000
	s_addc_u32 s11, s85, 0
	s_add_u32 s12, s84, 0x100000
	s_addc_u32 s13, s85, 0
	s_ashr_i32 s62, s82, 31
	s_add_u32 s14, s84, 0x140000
	s_addc_u32 s15, s85, 0
	s_add_u32 s16, s84, 0x180000
	s_addc_u32 s17, s85, 0
	s_add_u32 s18, s84, 0x1c0000
	s_addc_u32 s19, s85, 0
	s_add_u32 s20, s84, 0x200000
	s_addc_u32 s21, s85, 0
	s_add_u32 s22, s84, 0x240000
	s_addc_u32 s23, s85, 0
	s_add_u32 s24, s84, 0x280000
	s_addc_u32 s25, s85, 0
	s_add_u32 s26, s84, 0x2c0000
	s_addc_u32 s27, s85, 0
	s_and_b32 s1, s28, 3
	s_mov_b64 s[28:29], 0x80
	s_add_i32 m0, s57, 0x18000
	v_lshl_add_u64 v[6:7], v[6:7], 0, s[28:29]
	s_lshl_b32 s31, s30, 13
	s_lshl_b32 s35, s1, 12
	s_waitcnt vmcnt(2)
	s_barrier
	global_load_lds_dwordx4 v[6:7], off
	v_lshl_add_u64 v[4:5], v[4:5], 0, s[28:29]
	s_add_i32 m0, s57, 0x1a000
	s_add_i32 s63, s57, 0x8000
	s_add_i32 s64, s57, 0xa000
	global_load_lds_dwordx4 v[4:5], off
	v_lshl_add_u64 v[0:1], v[0:1], 0, s[28:29]
	s_mov_b32 m0, s63
	s_add_u32 s36, s48, 0x40080
	global_load_lds_dwordx4 v[0:1], off
	v_lshl_add_u64 v[0:1], v[2:3], 0, s[28:29]
	s_mov_b32 m0, s64
	s_addc_u32 s37, s49, 0
	global_load_lds_dwordx4 v[0:1], off
	s_add_i32 m0, s57, 0x1c000
	v_lshl_add_u64 v[0:1], s[36:37], 0, v[130:131]
	global_load_lds_dwordx4 v[0:1], off
	v_lshl_add_u64 v[0:1], s[36:37], 0, v[134:135]
	s_add_i32 m0, s57, 0x1e000
	s_movk_i32 s36, 0x3c0
	global_load_lds_dwordx4 v[0:1], off
	v_lshrrev_b32_e32 v0, 4, v182
	v_and_b32_e32 v4, 3, v0
	v_lshlrev_b32_e32 v6, 4, v4
	v_lshlrev_b32_e32 v0, 6, v182
	v_and_or_b32 v7, v0, s36, v6
	v_lshlrev_b32_e32 v0, 2, v182
	v_and_b32_e32 v1, 15, v182
	v_and_b32_e32 v12, 32, v0
	v_lshlrev_b32_e32 v0, 5, v4
	v_and_b32_e32 v136, 32, v0
	v_lshl_or_b32 v155, s30, 6, v1
	v_lshl_or_b32 v1, v1, 6, v6
	v_lshl_add_u64 v[2:3], s[84:85], 0, v[136:137]
	s_mov_b64 s[36:37], 0x1000
	v_bitop3_b32 v6, v1, s31, v12 bitop3:0xde
	v_mov_b32_e32 v1, v137
	v_lshl_add_u64 v[138:139], v[2:3], 0, s[36:37]
	v_lshl_add_u64 v[2:3], s[4:5], 0, v[0:1]
	s_movk_i32 s4, 0xffc0
	v_lshl_add_u64 v[0:1], s[6:7], 0, v[0:1]
	s_mov_b32 s5, -1
	v_lshl_add_u64 v[0:1], v[0:1], 0, s[4:5]
	v_cmp_gt_u32_e32 vcc, 2, v4
	s_cmpk_lt_u32 s34, 0x100
	s_cselect_b64 s[30:31], -1, 0
	v_cndmask_b32_e32 v140, v0, v2, vcc
	v_lshlrev_b32_e32 v0, 8, v182
	s_bitcmp0_b32 s34, 6
	v_cndmask_b32_e32 v141, v1, v3, vcc
	v_and_b32_e32 v0, 0x38000, v0
	v_lshlrev_b32_e32 v1, 11, v10
	v_bitop3_b32 v156, s35, v7, v12 bitop3:0xf6
	s_cselect_b64 s[34:35], -1, 0
	v_or3_b32 v0, v8, v0, v1
	s_and_b64 s[4:5], s[34:35], vcc
	v_add_u32_e32 v142, v0, v9
	v_lshlrev_b32_e32 v0, 4, v11
	s_waitcnt vmcnt(6)
	s_cmp_eq_u32 s1, 0
	v_and_b32_e32 v0, 0x78000, v0
	v_lshlrev_b32_e32 v5, 3, v4
	s_cselect_b64 s[34:35], -1, 0
	v_or3_b32 v0, v8, v0, v1
	s_add_i32 s66, 0, 0x10000
	s_add_i32 s67, 0, 0x14000
	v_lshlrev_b32_e32 v154, 19, v4
	v_lshl_or_b32 v157, s1, 5, v5
	v_mov_b32_e32 v143, v137
	v_add_u32_e32 v144, v0, v9
	v_mov_b32_e32 v145, v137
	v_mov_b64_e32 v[146:147], 0x1700
	v_mov_b64_e32 v[148:149], 0x16ff
	s_movk_i32 s65, 0x2e1
	v_add_u32_e32 v158, s66, v156
	v_add_u32_e32 v159, s67, v156
	v_add_u32_e32 v160, 0, v6
	s_movk_i32 s68, 0x2c00
	s_mov_b32 s69, 0x41700000
	s_mov_b32 s70, 0x3c23d70a
	s_mov_b32 s71, 0x800000
	s_mov_b32 s72, 0x3f317217
	s_mov_b32 s73, 0x7f800000
	s_mov_b32 s74, 0xbeaaaaab
	v_mov_b32_e32 v161, 0x41b17218
	s_barrier
	s_mov_b32 s88, 0
	s_branch .LBB0_472

.LBB0_475:
	ds_read_b128 v[150:153], v158
	ds_read_b128 v[162:165], v158 offset:1024
	ds_read_b128 v[166:169], v158 offset:2048
	ds_read_b128 v[170:173], v158 offset:3072
	ds_read_b128 v[174:177], v159
	ds_read_b128 v[178:181], v159 offset:1024
	ds_read_b128 v[184:187], v159 offset:2048
	ds_read_b128 v[188:191], v159 offset:3072
	s_add_u32 s48, s46, 0xfffc0080
	s_addc_u32 s49, s47, -1
	s_cmp_eq_u32 s77, 12
	s_cselect_b32 s51, s1, s49
	s_cselect_b32 s50, s39, s48
	s_cselect_b32 s49, s37, s76
	s_cselect_b32 s48, s45, s75
	v_lshl_add_u64 v[224:225], s[46:47], 0, v[142:143]
	s_add_i32 m0, s57, 0xc000
	ds_read_b128 v[192:195], v160
	ds_read_b128 v[196:199], v160 offset:1024
	ds_read_b128 v[200:203], v160 offset:2048
	ds_read_b128 v[204:207], v160 offset:3072
	ds_read_b128 v[208:211], v160 offset:4096
	ds_read_b128 v[212:215], v160 offset:5120
	ds_read_b128 v[216:219], v160 offset:6144
	ds_read_b128 v[220:223], v160 offset:7168
	global_load_lds_dwordx4 v[224:225], off
	v_lshl_add_u64 v[224:225], s[46:47], 0, v[144:145]
	s_add_i32 m0, s57, 0xe000
	s_nop 0
	global_load_lds_dwordx4 v[224:225], off
	s_cmp_eq_u32 s88, 1
	s_cbranch_scc1 .Lgw_4a
	s_waitcnt vmcnt(8)
.Lgw_4a:
	s_waitcnt vmcnt(24)
	s_waitcnt lgkmcnt(0)
	s_barrier
	s_setprio 1
	s_waitcnt lgkmcnt(0)
	v_mfma_f32_16x16x32_bf16 v[64:67], v[150:153], v[192:195], v[64:67]
	v_mfma_f32_16x16x32_bf16 v[28:31], v[166:169], v[192:195], v[28:31]
	v_mfma_f32_16x16x32_bf16 v[60:63], v[150:153], v[200:203], v[60:63]
	v_mfma_f32_16x16x32_bf16 v[24:27], v[166:169], v[200:203], v[24:27]
	v_mfma_f32_16x16x32_bf16 v[56:59], v[150:153], v[208:211], v[56:59]
	v_mfma_f32_16x16x32_bf16 v[20:23], v[166:169], v[208:211], v[20:23]
	v_mfma_f32_16x16x32_bf16 v[52:55], v[150:153], v[216:219], v[52:55]
	v_mfma_f32_16x16x32_bf16 v[16:19], v[166:169], v[216:219], v[16:19]
	v_mfma_f32_16x16x32_bf16 v[64:67], v[162:165], v[196:199], v[64:67]
	v_mfma_f32_16x16x32_bf16 v[28:31], v[170:173], v[196:199], v[28:31]
	v_mfma_f32_16x16x32_bf16 v[60:63], v[162:165], v[204:207], v[60:63]
	v_mfma_f32_16x16x32_bf16 v[24:27], v[170:173], v[204:207], v[24:27]
	v_mfma_f32_16x16x32_bf16 v[56:59], v[162:165], v[212:215], v[56:59]
	v_mfma_f32_16x16x32_bf16 v[20:23], v[170:173], v[212:215], v[20:23]
	v_mfma_f32_16x16x32_bf16 v[52:55], v[162:165], v[220:223], v[52:55]
	v_mfma_f32_16x16x32_bf16 v[16:19], v[170:173], v[220:223], v[16:19]
	s_setprio 0
	s_setprio 1
	v_mfma_f32_16x16x32_bf16 v[124:127], v[174:177], v[192:195], v[124:127]
	v_mfma_f32_16x16x32_bf16 v[120:123], v[184:187], v[192:195], v[120:123]
	v_mfma_f32_16x16x32_bf16 v[116:119], v[174:177], v[200:203], v[116:119]
	v_mfma_f32_16x16x32_bf16 v[112:115], v[184:187], v[200:203], v[112:115]
	v_mfma_f32_16x16x32_bf16 v[108:111], v[174:177], v[208:211], v[108:111]
	v_mfma_f32_16x16x32_bf16 v[104:107], v[184:187], v[208:211], v[104:107]
	v_mfma_f32_16x16x32_bf16 v[100:103], v[174:177], v[216:219], v[100:103]
	v_mfma_f32_16x16x32_bf16 v[96:99], v[184:187], v[216:219], v[96:99]
	v_mfma_f32_16x16x32_bf16 v[124:127], v[178:181], v[196:199], v[124:127]
	v_mfma_f32_16x16x32_bf16 v[120:123], v[188:191], v[196:199], v[120:123]
	v_mfma_f32_16x16x32_bf16 v[116:119], v[178:181], v[204:207], v[116:119]
	v_mfma_f32_16x16x32_bf16 v[112:115], v[188:191], v[204:207], v[112:115]
	v_mfma_f32_16x16x32_bf16 v[108:111], v[178:181], v[212:215], v[108:111]
	v_mfma_f32_16x16x32_bf16 v[104:107], v[188:191], v[212:215], v[104:107]
	v_mfma_f32_16x16x32_bf16 v[100:103], v[178:181], v[220:223], v[100:103]
	v_mfma_f32_16x16x32_bf16 v[96:99], v[188:191], v[220:223], v[96:99]
	s_setprio 0
	s_barrier
	s_add_i32 s78, s66, s56
	v_lshl_add_u64 v[224:225], s[48:49], 0, v[130:131]
	s_mov_b32 m0, s78
	ds_read_b128 v[192:195], v160 offset:16384
	ds_read_b128 v[196:199], v160 offset:17408
	ds_read_b128 v[200:203], v160 offset:18432
	ds_read_b128 v[204:207], v160 offset:19456
	ds_read_b128 v[208:211], v160 offset:20480
	ds_read_b128 v[212:215], v160 offset:21504
	ds_read_b128 v[216:219], v160 offset:22528
	ds_read_b128 v[220:223], v160 offset:23552
	global_load_lds_dwordx4 v[224:225], off
	s_add_i32 m0, s78, 0x2000
	s_add_u32 s78, s48, 0x40000
	v_lshl_add_u64 v[226:227], s[48:49], 0, v[134:135]
	s_addc_u32 s79, s49, 0
	s_add_i32 s80, s67, s56
	global_load_lds_dwordx4 v[226:227], off
	v_lshl_add_u64 v[228:229], s[78:79], 0, v[130:131]
	s_mov_b32 m0, s80
	v_lshl_add_u64 v[230:231], s[50:51], 0, v[132:133]
	global_load_lds_dwordx4 v[228:229], off
	v_lshl_add_u64 v[228:229], s[78:79], 0, v[134:135]
	s_add_i32 m0, s80, 0x2000
	s_nop 0
	global_load_lds_dwordx4 v[228:229], off
	v_lshl_add_u64 v[228:229], s[50:51], 0, v[128:129]
	s_mov_b32 m0, s57
	s_nop 0
	global_load_lds_dwordx4 v[228:229], off
	s_mov_b32 m0, s58
	s_nop 0
	global_load_lds_dwordx4 v[230:231], off
	s_cmp_eq_u32 s88, 1
	s_cbranch_scc1 .Lgw_4b
	s_waitcnt vmcnt(8)
.Lgw_4b:
	s_waitcnt vmcnt(24)
	s_waitcnt lgkmcnt(0)
	s_barrier
	s_mov_b32 s88, 0
	s_setprio 1
	s_waitcnt lgkmcnt(0)
	v_mfma_f32_16x16x32_bf16 v[44:47], v[150:153], v[192:195], v[44:47]
	v_mfma_f32_16x16x32_bf16 v[12:15], v[166:169], v[192:195], v[12:15]
	v_mfma_f32_16x16x32_bf16 v[40:43], v[150:153], v[200:203], v[40:43]
	v_mfma_f32_16x16x32_bf16 v[8:11], v[166:169], v[200:203], v[8:11]
	v_mfma_f32_16x16x32_bf16 v[36:39], v[150:153], v[208:211], v[36:39]
	v_mfma_f32_16x16x32_bf16 v[4:7], v[166:169], v[208:211], v[4:7]
	v_mfma_f32_16x16x32_bf16 v[32:35], v[150:153], v[216:219], v[32:35]
	v_mfma_f32_16x16x32_bf16 v[0:3], v[166:169], v[216:219], v[0:3]
	v_mfma_f32_16x16x32_bf16 v[44:47], v[162:165], v[196:199], v[44:47]
	v_mfma_f32_16x16x32_bf16 v[12:15], v[170:173], v[196:199], v[12:15]
	v_mfma_f32_16x16x32_bf16 v[40:43], v[162:165], v[204:207], v[40:43]
	v_mfma_f32_16x16x32_bf16 v[8:11], v[170:173], v[204:207], v[8:11]
	v_mfma_f32_16x16x32_bf16 v[36:39], v[162:165], v[212:215], v[36:39]
	v_mfma_f32_16x16x32_bf16 v[4:7], v[170:173], v[212:215], v[4:7]
	v_mfma_f32_16x16x32_bf16 v[32:35], v[162:165], v[220:223], v[32:35]
	v_mfma_f32_16x16x32_bf16 v[0:3], v[170:173], v[220:223], v[0:3]
	s_setprio 0
	s_setprio 1
	v_mfma_f32_16x16x32_bf16 v[92:95], v[174:177], v[192:195], v[92:95]
	v_mfma_f32_16x16x32_bf16 v[88:91], v[184:187], v[192:195], v[88:91]
	v_mfma_f32_16x16x32_bf16 v[84:87], v[174:177], v[200:203], v[84:87]
	v_mfma_f32_16x16x32_bf16 v[80:83], v[184:187], v[200:203], v[80:83]
	v_mfma_f32_16x16x32_bf16 v[76:79], v[174:177], v[208:211], v[76:79]
	v_mfma_f32_16x16x32_bf16 v[72:75], v[184:187], v[208:211], v[72:75]
	v_mfma_f32_16x16x32_bf16 v[68:71], v[174:177], v[216:219], v[68:71]
	v_mfma_f32_16x16x32_bf16 v[48:51], v[184:187], v[216:219], v[48:51]
	v_mfma_f32_16x16x32_bf16 v[92:95], v[178:181], v[196:199], v[92:95]
	v_mfma_f32_16x16x32_bf16 v[88:91], v[188:191], v[196:199], v[88:91]
	v_mfma_f32_16x16x32_bf16 v[84:87], v[178:181], v[204:207], v[84:87]
	v_mfma_f32_16x16x32_bf16 v[80:83], v[188:191], v[204:207], v[80:83]
	v_mfma_f32_16x16x32_bf16 v[76:79], v[178:181], v[212:215], v[76:79]
	v_mfma_f32_16x16x32_bf16 v[72:75], v[188:191], v[212:215], v[72:75]
	v_mfma_f32_16x16x32_bf16 v[68:71], v[178:181], v[220:223], v[68:71]
	v_mfma_f32_16x16x32_bf16 v[48:51], v[188:191], v[220:223], v[48:51]
	s_setprio 0
	s_barrier
	s_add_i32 s78, 0, 0x18000
	v_add_u32_e32 v136, s78, v156
	s_add_i32 s79, 0, 0x1c000
	ds_read_b128 v[150:153], v136
	ds_read_b128 v[162:165], v136 offset:1024
	ds_read_b128 v[166:169], v136 offset:2048
	ds_read_b128 v[170:173], v136 offset:3072
	v_add_u32_e32 v136, s79, v156
	ds_read_b128 v[174:177], v136
	ds_read_b128 v[178:181], v136 offset:1024
	ds_read_b128 v[184:187], v136 offset:2048
	ds_read_b128 v[188:191], v136 offset:3072
	s_add_u32 s50, s50, 0x40000
	s_addc_u32 s51, s51, 0
	s_mov_b32 m0, s59
	v_lshl_add_u64 v[232:233], s[50:51], 0, v[128:129]
	ds_read_b128 v[192:195], v160 offset:32768
	ds_read_b128 v[196:199], v160 offset:33792
	ds_read_b128 v[200:203], v160 offset:34816
	ds_read_b128 v[204:207], v160 offset:35840
	ds_read_b128 v[208:211], v160 offset:36864
	ds_read_b128 v[212:215], v160 offset:37888
	ds_read_b128 v[216:219], v160 offset:38912
	ds_read_b128 v[220:223], v160 offset:39936
	global_load_lds_dwordx4 v[232:233], off
	v_lshl_add_u64 v[232:233], s[50:51], 0, v[132:133]
	s_mov_b32 m0, s60
	s_nop 0
	global_load_lds_dwordx4 v[232:233], off
	s_waitcnt vmcnt(8)
	s_waitcnt lgkmcnt(0)
	s_barrier
	s_setprio 1
	s_waitcnt lgkmcnt(0)
	v_mfma_f32_16x16x32_bf16 v[64:67], v[150:153], v[192:195], v[64:67]
	v_mfma_f32_16x16x32_bf16 v[28:31], v[166:169], v[192:195], v[28:31]
	v_mfma_f32_16x16x32_bf16 v[60:63], v[150:153], v[200:203], v[60:63]
	v_mfma_f32_16x16x32_bf16 v[24:27], v[166:169], v[200:203], v[24:27]
	v_mfma_f32_16x16x32_bf16 v[56:59], v[150:153], v[208:211], v[56:59]
	v_mfma_f32_16x16x32_bf16 v[20:23], v[166:169], v[208:211], v[20:23]
	v_mfma_f32_16x16x32_bf16 v[52:55], v[150:153], v[216:219], v[52:55]
	v_mfma_f32_16x16x32_bf16 v[16:19], v[166:169], v[216:219], v[16:19]
	v_mfma_f32_16x16x32_bf16 v[64:67], v[162:165], v[196:199], v[64:67]
	v_mfma_f32_16x16x32_bf16 v[28:31], v[170:173], v[196:199], v[28:31]
	v_mfma_f32_16x16x32_bf16 v[60:63], v[162:165], v[204:207], v[60:63]
	v_mfma_f32_16x16x32_bf16 v[24:27], v[170:173], v[204:207], v[24:27]
	v_mfma_f32_16x16x32_bf16 v[56:59], v[162:165], v[212:215], v[56:59]
	v_mfma_f32_16x16x32_bf16 v[20:23], v[170:173], v[212:215], v[20:23]
	v_mfma_f32_16x16x32_bf16 v[52:55], v[162:165], v[220:223], v[52:55]
	v_mfma_f32_16x16x32_bf16 v[16:19], v[170:173], v[220:223], v[16:19]
	s_setprio 0
	s_setprio 1
	v_mfma_f32_16x16x32_bf16 v[124:127], v[174:177], v[192:195], v[124:127]
	v_mfma_f32_16x16x32_bf16 v[120:123], v[184:187], v[192:195], v[120:123]
	v_mfma_f32_16x16x32_bf16 v[116:119], v[174:177], v[200:203], v[116:119]
	v_mfma_f32_16x16x32_bf16 v[112:115], v[184:187], v[200:203], v[112:115]
	v_mfma_f32_16x16x32_bf16 v[108:111], v[174:177], v[208:211], v[108:111]
	v_mfma_f32_16x16x32_bf16 v[104:107], v[184:187], v[208:211], v[104:107]
	v_mfma_f32_16x16x32_bf16 v[100:103], v[174:177], v[216:219], v[100:103]
	v_mfma_f32_16x16x32_bf16 v[96:99], v[184:187], v[216:219], v[96:99]
	v_mfma_f32_16x16x32_bf16 v[124:127], v[178:181], v[196:199], v[124:127]
	v_mfma_f32_16x16x32_bf16 v[120:123], v[188:191], v[196:199], v[120:123]
	v_mfma_f32_16x16x32_bf16 v[116:119], v[178:181], v[204:207], v[116:119]
	v_mfma_f32_16x16x32_bf16 v[112:115], v[188:191], v[204:207], v[112:115]
	v_mfma_f32_16x16x32_bf16 v[108:111], v[178:181], v[212:215], v[108:111]
	v_mfma_f32_16x16x32_bf16 v[104:107], v[188:191], v[212:215], v[104:107]
	v_mfma_f32_16x16x32_bf16 v[100:103], v[178:181], v[220:223], v[100:103]
	v_mfma_f32_16x16x32_bf16 v[96:99], v[188:191], v[220:223], v[96:99]
	s_setprio 0
	s_barrier
	s_add_i32 s50, s78, s56
	v_lshl_add_u64 v[224:225], v[224:225], 0, s[28:29]
	s_mov_b32 m0, s50
	ds_read_b128 v[192:195], v160 offset:49152
	ds_read_b128 v[196:199], v160 offset:50176
	ds_read_b128 v[200:203], v160 offset:51200
	ds_read_b128 v[204:207], v160 offset:52224
	ds_read_b128 v[208:211], v160 offset:53248
	ds_read_b128 v[212:215], v160 offset:54272
	ds_read_b128 v[216:219], v160 offset:55296
	ds_read_b128 v[220:223], v160 offset:56320
	global_load_lds_dwordx4 v[224:225], off
	s_add_i32 m0, s50, 0x2000
	s_add_u32 s48, s48, 0x40080
	v_lshl_add_u64 v[224:225], v[226:227], 0, s[28:29]
	s_addc_u32 s49, s49, 0
	s_add_i32 s50, s79, s56
	global_load_lds_dwordx4 v[224:225], off
	v_lshl_add_u64 v[224:225], s[48:49], 0, v[130:131]
	s_mov_b32 m0, s50
	s_nop 0
	global_load_lds_dwordx4 v[224:225], off
	v_lshl_add_u64 v[224:225], s[48:49], 0, v[134:135]
	s_add_i32 m0, s50, 0x2000
	s_nop 0
	global_load_lds_dwordx4 v[224:225], off
	v_lshl_add_u64 v[224:225], v[228:229], 0, s[28:29]
	s_mov_b32 m0, s63
	s_nop 0
	global_load_lds_dwordx4 v[224:225], off
	v_lshl_add_u64 v[224:225], v[230:231], 0, s[28:29]
	s_mov_b32 m0, s64
	s_nop 0
	global_load_lds_dwordx4 v[224:225], off
	s_waitcnt vmcnt(8)
	s_waitcnt lgkmcnt(0)
	s_barrier
	s_setprio 1
	s_waitcnt lgkmcnt(0)
	v_mfma_f32_16x16x32_bf16 v[44:47], v[150:153], v[192:195], v[44:47]
	v_mfma_f32_16x16x32_bf16 v[12:15], v[166:169], v[192:195], v[12:15]
	v_mfma_f32_16x16x32_bf16 v[40:43], v[150:153], v[200:203], v[40:43]
	v_mfma_f32_16x16x32_bf16 v[8:11], v[166:169], v[200:203], v[8:11]
	v_mfma_f32_16x16x32_bf16 v[36:39], v[150:153], v[208:211], v[36:39]
	v_mfma_f32_16x16x32_bf16 v[4:7], v[166:169], v[208:211], v[4:7]
	v_mfma_f32_16x16x32_bf16 v[32:35], v[150:153], v[216:219], v[32:35]
	v_mfma_f32_16x16x32_bf16 v[0:3], v[166:169], v[216:219], v[0:3]
	v_mfma_f32_16x16x32_bf16 v[44:47], v[162:165], v[196:199], v[44:47]
	v_mfma_f32_16x16x32_bf16 v[12:15], v[170:173], v[196:199], v[12:15]
	v_mfma_f32_16x16x32_bf16 v[40:43], v[162:165], v[204:207], v[40:43]
	v_mfma_f32_16x16x32_bf16 v[8:11], v[170:173], v[204:207], v[8:11]
	v_mfma_f32_16x16x32_bf16 v[36:39], v[162:165], v[212:215], v[36:39]
	v_mfma_f32_16x16x32_bf16 v[4:7], v[170:173], v[212:215], v[4:7]
	v_mfma_f32_16x16x32_bf16 v[32:35], v[162:165], v[220:223], v[32:35]
	v_mfma_f32_16x16x32_bf16 v[0:3], v[170:173], v[220:223], v[0:3]
	s_setprio 0
	s_setprio 1
	v_mfma_f32_16x16x32_bf16 v[92:95], v[174:177], v[192:195], v[92:95]
	v_mfma_f32_16x16x32_bf16 v[88:91], v[184:187], v[192:195], v[88:91]
	v_mfma_f32_16x16x32_bf16 v[84:87], v[174:177], v[200:203], v[84:87]
	v_mfma_f32_16x16x32_bf16 v[80:83], v[184:187], v[200:203], v[80:83]
	v_mfma_f32_16x16x32_bf16 v[76:79], v[174:177], v[208:211], v[76:79]
	v_mfma_f32_16x16x32_bf16 v[72:75], v[184:187], v[208:211], v[72:75]
	v_mfma_f32_16x16x32_bf16 v[68:71], v[174:177], v[216:219], v[68:71]
	v_mfma_f32_16x16x32_bf16 v[48:51], v[184:187], v[216:219], v[48:51]
	v_mfma_f32_16x16x32_bf16 v[92:95], v[178:181], v[196:199], v[92:95]
	v_mfma_f32_16x16x32_bf16 v[88:91], v[188:191], v[196:199], v[88:91]
	v_mfma_f32_16x16x32_bf16 v[84:87], v[178:181], v[204:207], v[84:87]
	v_mfma_f32_16x16x32_bf16 v[80:83], v[188:191], v[204:207], v[80:83]
	v_mfma_f32_16x16x32_bf16 v[76:79], v[178:181], v[212:215], v[76:79]
	v_mfma_f32_16x16x32_bf16 v[72:75], v[188:191], v[212:215], v[72:75]
	v_mfma_f32_16x16x32_bf16 v[68:71], v[178:181], v[220:223], v[68:71]
	v_mfma_f32_16x16x32_bf16 v[48:51], v[188:191], v[220:223], v[48:51]
	s_setprio 0
	s_barrier
	s_add_i32 s77, s77, 2
	s_add_u32 s46, s46, 0x100
	s_addc_u32 s47, s47, 0
	s_add_u32 s75, s75, 0x100
	s_addc_u32 s76, s76, 0
	s_cmp_gt_u32 s77, 13
	s_cbranch_scc0 .LBB0_475
	s_and_b64 vcc, exec, s[30:31]
	s_cbranch_vccnz .LBB0_479
	v_lshl_add_u32 v162, s44, 8, v155
	s_cmp_lg_u32 s0, 22
	s_mov_b64 s[44:45], -1
	s_cbranch_scc1 .LBB0_480
.LBB0_478:
	s_mov_b32 s88, 0
	s_andn2_b64 vcc, exec, s[44:45]
	s_cbranch_vccz .LBB0_485
	s_branch .LBB0_486

.LBB0_480:
	s_mov_b32 s88, 1
	v_mov_b64_e32 v[150:151], s[10:11]
	v_lshl_or_b32 v136, s0, 8, v157
	s_cmp_lt_i32 s0, 8
	v_mad_i64_i32 v[152:153], s[0:1], v162, s68, v[150:151]
	s_mov_b64 s[0:1], -1
	v_or_b32_e32 v169, 16, v162
	v_or_b32_e32 v168, 32, v162
	v_or_b32_e32 v167, 48, v162
	v_add_u32_e32 v166, 0x80, v162
	v_add_u32_e32 v165, 0x90, v162
	v_add_u32_e32 v164, 0xa0, v162
	v_add_u32_e32 v163, 0xb0, v162
	s_cbranch_scc1 .LBB0_482
	v_lshlrev_b64 v[150:151], 1, v[136:137]
	v_lshl_add_u64 v[174:175], v[152:153], 0, v[150:151]
	v_cvt_pk_bf16_f32 v170, v64, v65
	v_cvt_pk_bf16_f32 v171, v66, v67
	v_cvt_pk_bf16_f32 v172, v28, v29
	v_cvt_pk_bf16_f32 v173, v30, v31
	global_store_dwordx4 v[174:175], v[170:173], off
	s_nop 1
	v_cvt_pk_bf16_f32 v170, v124, v125
	v_cvt_pk_bf16_f32 v171, v126, v127
	v_cvt_pk_bf16_f32 v172, v120, v121
	v_cvt_pk_bf16_f32 v173, v122, v123
	global_store_dwordx4 v[174:175], v[170:173], off offset:256
	v_mov_b64_e32 v[174:175], s[10:11]
	s_nop 0
	v_mad_i64_i32 v[170:171], s[0:1], v169, s68, v[174:175]
	v_lshl_add_u64 v[176:177], v[170:171], 0, v[150:151]
	v_cvt_pk_bf16_f32 v170, v60, v61
	v_cvt_pk_bf16_f32 v171, v62, v63
	v_cvt_pk_bf16_f32 v172, v24, v25
	v_cvt_pk_bf16_f32 v173, v26, v27
	global_store_dwordx4 v[176:177], v[170:173], off
	s_nop 1
	v_cvt_pk_bf16_f32 v170, v116, v117
	v_cvt_pk_bf16_f32 v171, v118, v119
	v_cvt_pk_bf16_f32 v172, v112, v113
	v_cvt_pk_bf16_f32 v173, v114, v115
	global_store_dwordx4 v[176:177], v[170:173], off offset:256
	s_nop 1
	v_mad_i64_i32 v[170:171], s[0:1], v168, s68, v[174:175]
	v_lshl_add_u64 v[176:177], v[170:171], 0, v[150:151]
	v_cvt_pk_bf16_f32 v170, v56, v57
	v_cvt_pk_bf16_f32 v171, v58, v59
	v_cvt_pk_bf16_f32 v172, v20, v21
	v_cvt_pk_bf16_f32 v173, v22, v23
	global_store_dwordx4 v[176:177], v[170:173], off
	s_nop 1
	v_cvt_pk_bf16_f32 v170, v108, v109
	v_cvt_pk_bf16_f32 v171, v110, v111
	v_cvt_pk_bf16_f32 v172, v104, v105
	v_cvt_pk_bf16_f32 v173, v106, v107
	global_store_dwordx4 v[176:177], v[170:173], off offset:256
	s_nop 1
	v_mad_i64_i32 v[170:171], s[0:1], v167, s68, v[174:175]
	v_lshl_add_u64 v[176:177], v[170:171], 0, v[150:151]
	v_cvt_pk_bf16_f32 v170, v52, v53
	v_cvt_pk_bf16_f32 v171, v54, v55
	v_cvt_pk_bf16_f32 v172, v16, v17
	v_cvt_pk_bf16_f32 v173, v18, v19
	global_store_dwordx4 v[176:177], v[170:173], off
	s_nop 1
	v_cvt_pk_bf16_f32 v170, v100, v101
	v_cvt_pk_bf16_f32 v171, v102, v103
	v_cvt_pk_bf16_f32 v172, v96, v97
	v_cvt_pk_bf16_f32 v173, v98, v99
	global_store_dwordx4 v[176:177], v[170:173], off offset:256
	s_nop 1
	v_mad_i64_i32 v[170:171], s[0:1], v166, s68, v[174:175]
	v_lshl_add_u64 v[176:177], v[170:171], 0, v[150:151]
	v_cvt_pk_bf16_f32 v170, v44, v45
	v_cvt_pk_bf16_f32 v171, v46, v47
	v_cvt_pk_bf16_f32 v172, v12, v13
	v_cvt_pk_bf16_f32 v173, v14, v15
	global_store_dwordx4 v[176:177], v[170:173], off
	s_nop 1
	v_cvt_pk_bf16_f32 v170, v92, v93
	v_cvt_pk_bf16_f32 v171, v94, v95
	v_cvt_pk_bf16_f32 v172, v88, v89
	v_cvt_pk_bf16_f32 v173, v90, v91
	global_store_dwordx4 v[176:177], v[170:173], off offset:256
	s_nop 1
	v_mad_i64_i32 v[170:171], s[0:1], v165, s68, v[174:175]
	v_lshl_add_u64 v[176:177], v[170:171], 0, v[150:151]
	v_cvt_pk_bf16_f32 v170, v40, v41
	v_cvt_pk_bf16_f32 v171, v42, v43
	v_cvt_pk_bf16_f32 v172, v8, v9
	v_cvt_pk_bf16_f32 v173, v10, v11
	global_store_dwordx4 v[176:177], v[170:173], off
	s_nop 1
	v_cvt_pk_bf16_f32 v170, v84, v85
	v_cvt_pk_bf16_f32 v171, v86, v87
	v_cvt_pk_bf16_f32 v172, v80, v81
	v_cvt_pk_bf16_f32 v173, v82, v83
	global_store_dwordx4 v[176:177], v[170:173], off offset:256
	s_nop 1
	v_mad_i64_i32 v[170:171], s[0:1], v164, s68, v[174:175]
	v_lshl_add_u64 v[176:177], v[170:171], 0, v[150:151]
	v_cvt_pk_bf16_f32 v170, v36, v37
	v_cvt_pk_bf16_f32 v171, v38, v39
	v_cvt_pk_bf16_f32 v172, v4, v5
	v_cvt_pk_bf16_f32 v173, v6, v7
	global_store_dwordx4 v[176:177], v[170:173], off
	s_nop 1
	v_cvt_pk_bf16_f32 v170, v76, v77
	v_cvt_pk_bf16_f32 v171, v78, v79
	v_cvt_pk_bf16_f32 v172, v72, v73
	v_cvt_pk_bf16_f32 v173, v74, v75
	global_store_dwordx4 v[176:177], v[170:173], off offset:256
	s_nop 1
	v_mad_i64_i32 v[170:171], s[0:1], v163, s68, v[174:175]
	v_lshl_add_u64 v[150:151], v[170:171], 0, v[150:151]
	v_cvt_pk_bf16_f32 v170, v32, v33
	v_cvt_pk_bf16_f32 v171, v34, v35
	v_cvt_pk_bf16_f32 v172, v0, v1
	v_cvt_pk_bf16_f32 v173, v2, v3
	global_store_dwordx4 v[150:151], v[170:173], off
	s_mov_b64 s[0:1], 0
	s_nop 0
	v_cvt_pk_bf16_f32 v170, v68, v69
	v_cvt_pk_bf16_f32 v171, v70, v71
	v_cvt_pk_bf16_f32 v172, v48, v49
	v_cvt_pk_bf16_f32 v173, v50, v51
	global_store_dwordx4 v[150:151], v[170:173], off offset:256

.LBB0_1262:
	s_add_u32 s8, s84, 0x4000000
	s_addc_u32 s9, s85, 0
	s_lshl_b32 s5, s5, 5
	s_mov_b64 s[10:11], 0x80
	s_and_b32 s5, s5, 0x60
	s_add_i32 m0, s39, 0x18000
	v_lshl_add_u64 v[6:7], v[6:7], 0, s[10:11]
	s_ashr_i32 s44, s82, 31
	s_lshl_b32 s14, s4, 13
	s_lshl_b32 s15, s5, 7
	s_waitcnt vmcnt(2)
	s_barrier
	global_load_lds_dwordx4 v[6:7], off
	v_lshl_add_u64 v[4:5], v[4:5], 0, s[10:11]
	s_add_i32 m0, s39, 0x1a000
	s_add_i32 s45, s39, 0x8000
	s_add_i32 s46, s39, 0xa000
	global_load_lds_dwordx4 v[4:5], off
	v_lshl_add_u64 v[0:1], v[0:1], 0, s[10:11]
	s_mov_b32 m0, s45
	s_add_u32 s12, s28, 0x80080
	global_load_lds_dwordx4 v[0:1], off
	v_lshl_add_u64 v[0:1], v[2:3], 0, s[10:11]
	s_mov_b32 m0, s46
	s_addc_u32 s13, s29, 0
	global_load_lds_dwordx4 v[0:1], off
	s_add_i32 m0, s39, 0x1c000
	v_lshl_add_u64 v[0:1], s[12:13], 0, v[130:131]
	global_load_lds_dwordx4 v[0:1], off
	v_lshl_add_u64 v[0:1], s[12:13], 0, v[134:135]
	s_add_i32 m0, s39, 0x1e000
	s_sext_i32_i8 s55, s0
	global_load_lds_dwordx4 v[0:1], off
	v_and_b32_e32 v0, 15, v182
	v_lshlrev_b32_e32 v1, 1, v10
	v_lshlrev_b32_e32 v2, 6, v182
	s_movk_i32 s0, 0x3c0
	v_lshlrev_b32_e32 v3, 2, v182
	v_and_or_b32 v2, v2, s0, v1
	v_and_b32_e32 v3, 32, v3
	v_lshl_or_b32 v144, s4, 6, v0
	v_lshl_or_b32 v0, v0, 6, v1
	s_waitcnt vmcnt(6)
	s_cmpk_lt_u32 s1, 0x100
	v_add_u16_e32 v1, v8, v9
	v_bitop3_b32 v0, v0, s14, v3 bitop3:0xde
	v_bitop3_b32 v145, s15, v2, v3 bitop3:0xf6
	s_cselect_b64 s[12:13], -1, 0
	v_lshrrev_b16_e32 v1, 1, v1
	s_add_i32 s47, 0, 0x10000
	s_add_i32 s48, 0, 0x14000
	v_or_b32_e32 v146, s5, v10
	v_add_lshl_u32 v136, v11, v1, 1
	v_mov_b32_e32 v137, v131
	v_add_lshl_u32 v138, v12, v1, 1
	v_mov_b32_e32 v139, v131
	v_mov_b64_e32 v[140:141], 0x400
	v_mov_b64_e32 v[142:143], 0x3ff
	v_add_u32_e32 v147, s47, v145
	v_add_u32_e32 v148, s48, v145
	v_add_u32_e32 v149, 0, v0
	s_mov_b64 s[14:15], 0x40000
	s_mov_b32 s49, 0x40000
	s_mov_b64 s[16:17], 0x48000
	s_mov_b32 s50, 0x48000
	s_mov_b64 s[18:19], 0x50000
	s_mov_b32 s51, 0x50000
	s_mov_b64 s[20:21], 0x58000
	s_mov_b32 s52, 0x58000
	s_barrier
	s_mov_b32 s88, 0
	s_branch .LBB0_1265

.LBB0_1264:
	s_mov_b32 s88, 1
	s_andn2_b64 vcc, exec, s[0:1]
	s_mov_b32 s55, s22
	s_mov_b32 s53, s54
	s_mov_b64 s[28:29], s[26:27]
	s_mov_b64 s[30:31], s[24:25]
	s_cbranch_vccz .LBB0_1280

.LBB0_1274:
	ds_read_b128 v[150:153], v147
	ds_read_b128 v[154:157], v147 offset:1024
	ds_read_b128 v[158:161], v147 offset:2048
	ds_read_b128 v[162:165], v147 offset:3072
	ds_read_b128 v[166:169], v148
	ds_read_b128 v[170:173], v148 offset:1024
	ds_read_b128 v[174:177], v148 offset:2048
	ds_read_b128 v[178:181], v148 offset:3072
	s_add_u32 s28, s4, 0xffea0080
	s_addc_u32 s29, s5, -1
	s_cmp_eq_u32 s59, 28
	s_cselect_b32 s31, s25, s29
	s_cselect_b32 s30, s24, s28
	s_cselect_b32 s29, s23, s58
	s_cselect_b32 s28, s56, s57
	v_lshl_add_u64 v[216:217], s[4:5], 0, v[136:137]
	s_add_i32 m0, s39, 0xc000
	ds_read_b128 v[184:187], v149
	ds_read_b128 v[188:191], v149 offset:1024
	ds_read_b128 v[192:195], v149 offset:2048
	ds_read_b128 v[196:199], v149 offset:3072
	ds_read_b128 v[200:203], v149 offset:4096
	ds_read_b128 v[204:207], v149 offset:5120
	ds_read_b128 v[208:211], v149 offset:6144
	ds_read_b128 v[212:215], v149 offset:7168
	global_load_lds_dwordx4 v[216:217], off
	v_lshl_add_u64 v[216:217], s[4:5], 0, v[138:139]
	s_add_i32 m0, s39, 0xe000
	s_nop 0
	global_load_lds_dwordx4 v[216:217], off
	s_cmp_eq_u32 s88, 1
	s_cbranch_scc1 .Lgw_8a
	s_waitcnt vmcnt(8)
.Lgw_8a:
	s_waitcnt vmcnt(24)
	s_waitcnt lgkmcnt(0)
	s_barrier
	s_setprio 1
	s_waitcnt lgkmcnt(0)
	v_mfma_f32_16x16x32_bf16 v[124:127], v[150:153], v[184:187], v[124:127]
	v_mfma_f32_16x16x32_bf16 v[120:123], v[158:161], v[184:187], v[120:123]
	v_mfma_f32_16x16x32_bf16 v[116:119], v[150:153], v[192:195], v[116:119]
	v_mfma_f32_16x16x32_bf16 v[112:115], v[158:161], v[192:195], v[112:115]
	v_mfma_f32_16x16x32_bf16 v[100:103], v[150:153], v[200:203], v[100:103]
	v_mfma_f32_16x16x32_bf16 v[96:99], v[158:161], v[200:203], v[96:99]
	v_mfma_f32_16x16x32_bf16 v[84:87], v[150:153], v[208:211], v[84:87]
	v_mfma_f32_16x16x32_bf16 v[80:83], v[158:161], v[208:211], v[80:83]
	v_mfma_f32_16x16x32_bf16 v[124:127], v[154:157], v[188:191], v[124:127]
	v_mfma_f32_16x16x32_bf16 v[120:123], v[162:165], v[188:191], v[120:123]
	v_mfma_f32_16x16x32_bf16 v[116:119], v[154:157], v[196:199], v[116:119]
	v_mfma_f32_16x16x32_bf16 v[112:115], v[162:165], v[196:199], v[112:115]
	v_mfma_f32_16x16x32_bf16 v[100:103], v[154:157], v[204:207], v[100:103]
	v_mfma_f32_16x16x32_bf16 v[96:99], v[162:165], v[204:207], v[96:99]
	v_mfma_f32_16x16x32_bf16 v[84:87], v[154:157], v[212:215], v[84:87]
	v_mfma_f32_16x16x32_bf16 v[80:83], v[162:165], v[212:215], v[80:83]
	s_setprio 0
	s_setprio 1
	v_mfma_f32_16x16x32_bf16 v[108:111], v[166:169], v[184:187], v[108:111]
	v_mfma_f32_16x16x32_bf16 v[104:107], v[174:177], v[184:187], v[104:107]
	v_mfma_f32_16x16x32_bf16 v[92:95], v[166:169], v[192:195], v[92:95]
	v_mfma_f32_16x16x32_bf16 v[88:91], v[174:177], v[192:195], v[88:91]
	v_mfma_f32_16x16x32_bf16 v[76:79], v[166:169], v[200:203], v[76:79]
	v_mfma_f32_16x16x32_bf16 v[72:75], v[174:177], v[200:203], v[72:75]
	v_mfma_f32_16x16x32_bf16 v[68:71], v[166:169], v[208:211], v[68:71]
	v_mfma_f32_16x16x32_bf16 v[64:67], v[174:177], v[208:211], v[64:67]
	v_mfma_f32_16x16x32_bf16 v[108:111], v[170:173], v[188:191], v[108:111]
	v_mfma_f32_16x16x32_bf16 v[104:107], v[178:181], v[188:191], v[104:107]
	v_mfma_f32_16x16x32_bf16 v[92:95], v[170:173], v[196:199], v[92:95]
	v_mfma_f32_16x16x32_bf16 v[88:91], v[178:181], v[196:199], v[88:91]
	v_mfma_f32_16x16x32_bf16 v[76:79], v[170:173], v[204:207], v[76:79]
	v_mfma_f32_16x16x32_bf16 v[72:75], v[178:181], v[204:207], v[72:75]
	v_mfma_f32_16x16x32_bf16 v[68:71], v[170:173], v[212:215], v[68:71]
	v_mfma_f32_16x16x32_bf16 v[64:67], v[178:181], v[212:215], v[64:67]
	s_setprio 0
	s_barrier
	s_add_i32 s60, s47, s38
	v_lshl_add_u64 v[216:217], s[28:29], 0, v[130:131]
	s_mov_b32 m0, s60
	ds_read_b128 v[184:187], v149 offset:16384
	ds_read_b128 v[188:191], v149 offset:17408
	ds_read_b128 v[192:195], v149 offset:18432
	ds_read_b128 v[196:199], v149 offset:19456
	ds_read_b128 v[200:203], v149 offset:20480
	ds_read_b128 v[204:207], v149 offset:21504
	ds_read_b128 v[208:211], v149 offset:22528
	ds_read_b128 v[212:215], v149 offset:23552
	global_load_lds_dwordx4 v[216:217], off
	s_add_i32 m0, s60, 0x2000
	s_add_u32 s60, s28, 0x80000
	v_lshl_add_u64 v[218:219], s[28:29], 0, v[134:135]
	s_addc_u32 s61, s29, 0
	s_add_i32 s62, s48, s38
	global_load_lds_dwordx4 v[218:219], off
	v_lshl_add_u64 v[220:221], s[60:61], 0, v[130:131]
	s_mov_b32 m0, s62
	v_lshl_add_u64 v[222:223], s[30:31], 0, v[132:133]
	global_load_lds_dwordx4 v[220:221], off
	v_lshl_add_u64 v[220:221], s[60:61], 0, v[134:135]
	s_add_i32 m0, s62, 0x2000
	s_nop 0
	global_load_lds_dwordx4 v[220:221], off
	v_lshl_add_u64 v[220:221], s[30:31], 0, v[128:129]
	s_mov_b32 m0, s39
	s_nop 0
	global_load_lds_dwordx4 v[220:221], off
	s_mov_b32 m0, s40
	s_nop 0
	global_load_lds_dwordx4 v[222:223], off
	s_cmp_eq_u32 s88, 1
	s_cbranch_scc1 .Lgw_8b
	s_waitcnt vmcnt(8)
.Lgw_8b:
	s_waitcnt vmcnt(24)
	s_waitcnt lgkmcnt(0)
	s_barrier
	s_mov_b32 s88, 0
	s_setprio 1
	s_waitcnt lgkmcnt(0)
	v_mfma_f32_16x16x32_bf16 v[60:63], v[150:153], v[184:187], v[60:63]
	v_mfma_f32_16x16x32_bf16 v[56:59], v[158:161], v[184:187], v[56:59]
	v_mfma_f32_16x16x32_bf16 v[52:55], v[150:153], v[192:195], v[52:55]
	v_mfma_f32_16x16x32_bf16 v[48:51], v[158:161], v[192:195], v[48:51]
	v_mfma_f32_16x16x32_bf16 v[36:39], v[150:153], v[200:203], v[36:39]
	v_mfma_f32_16x16x32_bf16 v[32:35], v[158:161], v[200:203], v[32:35]
	v_mfma_f32_16x16x32_bf16 v[20:23], v[150:153], v[208:211], v[20:23]
	v_mfma_f32_16x16x32_bf16 v[16:19], v[158:161], v[208:211], v[16:19]
	v_mfma_f32_16x16x32_bf16 v[60:63], v[154:157], v[188:191], v[60:63]
	v_mfma_f32_16x16x32_bf16 v[56:59], v[162:165], v[188:191], v[56:59]
	v_mfma_f32_16x16x32_bf16 v[52:55], v[154:157], v[196:199], v[52:55]
	v_mfma_f32_16x16x32_bf16 v[48:51], v[162:165], v[196:199], v[48:51]
	v_mfma_f32_16x16x32_bf16 v[36:39], v[154:157], v[204:207], v[36:39]
	v_mfma_f32_16x16x32_bf16 v[32:35], v[162:165], v[204:207], v[32:35]
	v_mfma_f32_16x16x32_bf16 v[20:23], v[154:157], v[212:215], v[20:23]
	v_mfma_f32_16x16x32_bf16 v[16:19], v[162:165], v[212:215], v[16:19]
	s_setprio 0
	s_setprio 1
	v_mfma_f32_16x16x32_bf16 v[44:47], v[166:169], v[184:187], v[44:47]
	v_mfma_f32_16x16x32_bf16 v[40:43], v[174:177], v[184:187], v[40:43]
	v_mfma_f32_16x16x32_bf16 v[28:31], v[166:169], v[192:195], v[28:31]
	v_mfma_f32_16x16x32_bf16 v[24:27], v[174:177], v[192:195], v[24:27]
	v_mfma_f32_16x16x32_bf16 v[12:15], v[166:169], v[200:203], v[12:15]
	v_mfma_f32_16x16x32_bf16 v[8:11], v[174:177], v[200:203], v[8:11]
	v_mfma_f32_16x16x32_bf16 v[4:7], v[166:169], v[208:211], v[4:7]
	v_mfma_f32_16x16x32_bf16 v[0:3], v[174:177], v[208:211], v[0:3]
	v_mfma_f32_16x16x32_bf16 v[44:47], v[170:173], v[188:191], v[44:47]
	v_mfma_f32_16x16x32_bf16 v[40:43], v[178:181], v[188:191], v[40:43]
	v_mfma_f32_16x16x32_bf16 v[28:31], v[170:173], v[196:199], v[28:31]
	v_mfma_f32_16x16x32_bf16 v[24:27], v[178:181], v[196:199], v[24:27]
	v_mfma_f32_16x16x32_bf16 v[12:15], v[170:173], v[204:207], v[12:15]
	v_mfma_f32_16x16x32_bf16 v[8:11], v[178:181], v[204:207], v[8:11]
	v_mfma_f32_16x16x32_bf16 v[4:7], v[170:173], v[212:215], v[4:7]
	v_mfma_f32_16x16x32_bf16 v[0:3], v[178:181], v[212:215], v[0:3]
	s_setprio 0
	s_barrier
	s_add_i32 s60, 0, 0x18000
	s_add_i32 s61, 0, 0x1c000
	v_add_u32_e32 v162, s60, v145
	v_add_u32_e32 v178, s61, v145
	ds_read_b128 v[150:153], v162
	ds_read_b128 v[154:157], v162 offset:1024
	ds_read_b128 v[158:161], v162 offset:2048
	ds_read_b128 v[162:165], v162 offset:3072
	ds_read_b128 v[166:169], v178
	ds_read_b128 v[170:173], v178 offset:1024
	ds_read_b128 v[174:177], v178 offset:2048
	ds_read_b128 v[178:181], v178 offset:3072
	s_add_u32 s30, s30, 0x160000
	s_addc_u32 s31, s31, 0
	s_mov_b32 m0, s41
	v_lshl_add_u64 v[224:225], s[30:31], 0, v[128:129]
	ds_read_b128 v[184:187], v149 offset:32768
	ds_read_b128 v[188:191], v149 offset:33792
	ds_read_b128 v[192:195], v149 offset:34816
	ds_read_b128 v[196:199], v149 offset:35840
	ds_read_b128 v[200:203], v149 offset:36864
	ds_read_b128 v[204:207], v149 offset:37888
	ds_read_b128 v[208:211], v149 offset:38912
	ds_read_b128 v[212:215], v149 offset:39936
	global_load_lds_dwordx4 v[224:225], off
	v_lshl_add_u64 v[224:225], s[30:31], 0, v[132:133]
	s_mov_b32 m0, s42
	s_nop 0
	global_load_lds_dwordx4 v[224:225], off
	s_waitcnt vmcnt(8)
	s_waitcnt lgkmcnt(0)
	s_barrier
	s_setprio 1
	s_waitcnt lgkmcnt(0)
	v_mfma_f32_16x16x32_bf16 v[124:127], v[150:153], v[184:187], v[124:127]
	v_mfma_f32_16x16x32_bf16 v[120:123], v[158:161], v[184:187], v[120:123]
	v_mfma_f32_16x16x32_bf16 v[116:119], v[150:153], v[192:195], v[116:119]
	v_mfma_f32_16x16x32_bf16 v[112:115], v[158:161], v[192:195], v[112:115]
	v_mfma_f32_16x16x32_bf16 v[100:103], v[150:153], v[200:203], v[100:103]
	v_mfma_f32_16x16x32_bf16 v[96:99], v[158:161], v[200:203], v[96:99]
	v_mfma_f32_16x16x32_bf16 v[84:87], v[150:153], v[208:211], v[84:87]
	v_mfma_f32_16x16x32_bf16 v[80:83], v[158:161], v[208:211], v[80:83]
	v_mfma_f32_16x16x32_bf16 v[124:127], v[154:157], v[188:191], v[124:127]
	v_mfma_f32_16x16x32_bf16 v[120:123], v[162:165], v[188:191], v[120:123]
	v_mfma_f32_16x16x32_bf16 v[116:119], v[154:157], v[196:199], v[116:119]
	v_mfma_f32_16x16x32_bf16 v[112:115], v[162:165], v[196:199], v[112:115]
	v_mfma_f32_16x16x32_bf16 v[100:103], v[154:157], v[204:207], v[100:103]
	v_mfma_f32_16x16x32_bf16 v[96:99], v[162:165], v[204:207], v[96:99]
	v_mfma_f32_16x16x32_bf16 v[84:87], v[154:157], v[212:215], v[84:87]
	v_mfma_f32_16x16x32_bf16 v[80:83], v[162:165], v[212:215], v[80:83]
	s_setprio 0
	s_setprio 1
	v_mfma_f32_16x16x32_bf16 v[108:111], v[166:169], v[184:187], v[108:111]
	v_mfma_f32_16x16x32_bf16 v[104:107], v[174:177], v[184:187], v[104:107]
	v_mfma_f32_16x16x32_bf16 v[92:95], v[166:169], v[192:195], v[92:95]
	v_mfma_f32_16x16x32_bf16 v[88:91], v[174:177], v[192:195], v[88:91]
	v_mfma_f32_16x16x32_bf16 v[76:79], v[166:169], v[200:203], v[76:79]
	v_mfma_f32_16x16x32_bf16 v[72:75], v[174:177], v[200:203], v[72:75]
	v_mfma_f32_16x16x32_bf16 v[68:71], v[166:169], v[208:211], v[68:71]
	v_mfma_f32_16x16x32_bf16 v[64:67], v[174:177], v[208:211], v[64:67]
	v_mfma_f32_16x16x32_bf16 v[108:111], v[170:173], v[188:191], v[108:111]
	v_mfma_f32_16x16x32_bf16 v[104:107], v[178:181], v[188:191], v[104:107]
	v_mfma_f32_16x16x32_bf16 v[92:95], v[170:173], v[196:199], v[92:95]
	v_mfma_f32_16x16x32_bf16 v[88:91], v[178:181], v[196:199], v[88:91]
	v_mfma_f32_16x16x32_bf16 v[76:79], v[170:173], v[204:207], v[76:79]
	v_mfma_f32_16x16x32_bf16 v[72:75], v[178:181], v[204:207], v[72:75]
	v_mfma_f32_16x16x32_bf16 v[68:71], v[170:173], v[212:215], v[68:71]
	v_mfma_f32_16x16x32_bf16 v[64:67], v[178:181], v[212:215], v[64:67]
	s_setprio 0
	s_barrier
	s_add_i32 s30, s60, s38
	v_lshl_add_u64 v[216:217], v[216:217], 0, s[10:11]
	s_mov_b32 m0, s30
	ds_read_b128 v[184:187], v149 offset:49152
	ds_read_b128 v[188:191], v149 offset:50176
	ds_read_b128 v[192:195], v149 offset:51200
	ds_read_b128 v[196:199], v149 offset:52224
	ds_read_b128 v[200:203], v149 offset:53248
	ds_read_b128 v[204:207], v149 offset:54272
	ds_read_b128 v[208:211], v149 offset:55296
	ds_read_b128 v[212:215], v149 offset:56320
	global_load_lds_dwordx4 v[216:217], off
	s_add_i32 m0, s30, 0x2000
	s_add_u32 s28, s28, 0x80080
	v_lshl_add_u64 v[216:217], v[218:219], 0, s[10:11]
	s_addc_u32 s29, s29, 0
	s_add_i32 s30, s61, s38
	global_load_lds_dwordx4 v[216:217], off
	v_lshl_add_u64 v[216:217], s[28:29], 0, v[130:131]
	s_mov_b32 m0, s30
	s_nop 0
	global_load_lds_dwordx4 v[216:217], off
	v_lshl_add_u64 v[216:217], s[28:29], 0, v[134:135]
	s_add_i32 m0, s30, 0x2000
	s_nop 0
	global_load_lds_dwordx4 v[216:217], off
	v_lshl_add_u64 v[216:217], v[220:221], 0, s[10:11]
	s_mov_b32 m0, s45
	s_nop 0
	global_load_lds_dwordx4 v[216:217], off
	v_lshl_add_u64 v[216:217], v[222:223], 0, s[10:11]
	s_mov_b32 m0, s46
	s_nop 0
	global_load_lds_dwordx4 v[216:217], off
	s_waitcnt vmcnt(8)
	s_waitcnt lgkmcnt(0)
	s_barrier
	s_setprio 1
	s_waitcnt lgkmcnt(0)
	v_mfma_f32_16x16x32_bf16 v[60:63], v[150:153], v[184:187], v[60:63]
	v_mfma_f32_16x16x32_bf16 v[56:59], v[158:161], v[184:187], v[56:59]
	v_mfma_f32_16x16x32_bf16 v[52:55], v[150:153], v[192:195], v[52:55]
	v_mfma_f32_16x16x32_bf16 v[48:51], v[158:161], v[192:195], v[48:51]
	v_mfma_f32_16x16x32_bf16 v[36:39], v[150:153], v[200:203], v[36:39]
	v_mfma_f32_16x16x32_bf16 v[32:35], v[158:161], v[200:203], v[32:35]
	v_mfma_f32_16x16x32_bf16 v[20:23], v[150:153], v[208:211], v[20:23]
	v_mfma_f32_16x16x32_bf16 v[16:19], v[158:161], v[208:211], v[16:19]
	v_mfma_f32_16x16x32_bf16 v[60:63], v[154:157], v[188:191], v[60:63]
	v_mfma_f32_16x16x32_bf16 v[56:59], v[162:165], v[188:191], v[56:59]
	v_mfma_f32_16x16x32_bf16 v[52:55], v[154:157], v[196:199], v[52:55]
	v_mfma_f32_16x16x32_bf16 v[48:51], v[162:165], v[196:199], v[48:51]
	v_mfma_f32_16x16x32_bf16 v[36:39], v[154:157], v[204:207], v[36:39]
	v_mfma_f32_16x16x32_bf16 v[32:35], v[162:165], v[204:207], v[32:35]
	v_mfma_f32_16x16x32_bf16 v[20:23], v[154:157], v[212:215], v[20:23]
	v_mfma_f32_16x16x32_bf16 v[16:19], v[162:165], v[212:215], v[16:19]
	s_setprio 0
	s_setprio 1
	v_mfma_f32_16x16x32_bf16 v[44:47], v[166:169], v[184:187], v[44:47]
	v_mfma_f32_16x16x32_bf16 v[40:43], v[174:177], v[184:187], v[40:43]
	v_mfma_f32_16x16x32_bf16 v[28:31], v[166:169], v[192:195], v[28:31]
	v_mfma_f32_16x16x32_bf16 v[24:27], v[174:177], v[192:195], v[24:27]
	v_mfma_f32_16x16x32_bf16 v[12:15], v[166:169], v[200:203], v[12:15]
	v_mfma_f32_16x16x32_bf16 v[8:11], v[174:177], v[200:203], v[8:11]
	v_mfma_f32_16x16x32_bf16 v[4:7], v[166:169], v[208:211], v[4:7]
	v_mfma_f32_16x16x32_bf16 v[0:3], v[174:177], v[208:211], v[0:3]
	v_mfma_f32_16x16x32_bf16 v[44:47], v[170:173], v[188:191], v[44:47]
	v_mfma_f32_16x16x32_bf16 v[40:43], v[178:181], v[188:191], v[40:43]
	v_mfma_f32_16x16x32_bf16 v[28:31], v[170:173], v[196:199], v[28:31]
	v_mfma_f32_16x16x32_bf16 v[24:27], v[178:181], v[196:199], v[24:27]
	v_mfma_f32_16x16x32_bf16 v[12:15], v[170:173], v[204:207], v[12:15]
	v_mfma_f32_16x16x32_bf16 v[8:11], v[178:181], v[204:207], v[8:11]
	v_mfma_f32_16x16x32_bf16 v[4:7], v[170:173], v[212:215], v[4:7]
	v_mfma_f32_16x16x32_bf16 v[0:3], v[178:181], v[212:215], v[0:3]
	s_setprio 0
	s_barrier
	s_add_i32 s59, s59, 2
	s_add_u32 s4, s4, 0x100
	s_addc_u32 s5, s5, 0
	s_add_u32 s57, s57, 0x100
	s_addc_u32 s58, s58, 0
	s_cmp_gt_u32 s59, 29
	s_cbranch_scc0 .LBB0_1274
	s_and_b64 vcc, exec, s[12:13]
	s_cbranch_vccz .LBB0_1277
	s_barrier
